# v74 + nt policy on the row phases f32 residual-stream loads/stores (x/out are not re-read before >256MB of other traffic), keeping RAW/H in L2/MALL
# speedup vs baseline: 1.0245x; 1.0177x over previous
; #define LAS __attribute__((address_space(3)))
; __device__ __forceinline__ unsigned cvt_pk_bf16(float lo, float hi) { unsigned r; asm volatile("v_cvt_pk_bf16_f32 %0, %1, %2" : "=v"(r) : "v"(lo), "v"(hi)); return r; }
; template <bool POST, bool PRE>
; __device__ __forceinline__ void row_core(const Params& P, const RowCfg& c, LAS float* vA, LAS float* vB, LAS float* vP, const bf16_t* RAW, const float* SSQ, bf16_t* H, int row, int lane, f32x4 (&v)[8]) {
;     const f32x4* xs = (const f32x4*)(c.xsrc + (size_t)row * DM) + lane;
; #pragma unroll
;     for (int j = 0; j < 8; ++j) v[j] = xs[64 * j];
;     ...
;         float s2 = 0.f;
; #pragma unroll
;         for (int j = 0; j < 8; ++j) s2 += (v[j][0] * v[j][0] + v[j][1] * v[j][1]) + (v[j][2] * v[j][2] + v[j][3] * v[j][3]);
;         s2 = wave_sum(s2);
;         const float rstd2 = rsqrtf(s2 * (1.0f / DM) + EPS);
;         u32x2* hs = (u32x2*)(H + (size_t)row * DM) + lane;
; #pragma unroll
;         for (int j = 0; j < 8; ++j) { const f32x4 a = *(const LAS f32x4*)(vA + j * 256 + lane * 4), b = *(const LAS f32x4*)(vB + j * 256 + lane * 4);
;             v[j] = v[j] * rstd2 * a + b; u32x2 w; w.x = cvt_pk_bf16(v[j][0], v[j][1]); w.y = cvt_pk_bf16(v[j][2], v[j][3]); hs[64 * j] = w; }
; template <bool POST, bool PRE, bool THIN>
; __device__ __forceinline__ void row_phase(const Ctx& F, const RowCfg c) {
;     ...
;         for (int row = gw; row < SEQ; row += 2 * NGW) {
;             f32x4 v0[8], v1[8];
;             const int rowB = row + NGW; const bool hasB = rowB < SEQ;
;             row_core<POST, PRE>(P, c, vA, vB, vP, RAW, SSQ, H, row, lane, v0);
;             if (hasB) row_core<POST, PRE>(P, c, vA, vB, vP, RAW, SSQ, H, rowB, lane, v1);
.LBB0_184:
	s_add_i32 s16, s14, s3
	s_cmpk_lt_i32 s16, 0x4000
	s_cselect_b64 s[18:19], -1, 0
	s_ashr_i32 s15, s14, 31
	s_lshl_b64 s[20:21], s[14:15], 13
	s_waitcnt lgkmcnt(0)
	v_lshl_add_u64 v[0:1], v[32:33], 0, s[20:21]
	global_load_dwordx4 v[28:31], v[0:1], off nt
	global_load_dwordx4 v[24:27], v[0:1], off offset:1024 nt
	global_load_dwordx4 v[20:23], v[0:1], off offset:2048 nt
	global_load_dwordx4 v[16:19], v[0:1], off offset:3072 nt
	v_add_co_u32_e32 v4, vcc, s22, v0
	s_lshl_b64 s[20:21], s[14:15], 12
	s_nop 0
	v_addc_co_u32_e32 v5, vcc, 0, v1, vcc
	global_load_dwordx4 v[12:15], v[4:5], off nt
	global_load_dwordx4 v[8:11], v[4:5], off offset:1024 nt
	global_load_dwordx4 v[0:3], v[4:5], off offset:3072 nt
	s_nop 0
	global_load_dwordx4 v[4:7], v[4:5], off offset:2048 nt
	v_lshl_add_u64 v[68:69], v[34:35], 0, s[20:21]
	v_mov_b32_e32 v61, 0
	v_mov_b32_e32 v62, 0
	v_mov_b32_e32 v63, 0
	v_mov_b32_e32 v64, 0
	v_mov_b32_e32 v65, 0
	s_cmpk_gt_i32 s16, 0x3fff
	v_mov_b32_e32 v74, 0
	v_mov_b32_e32 v75, 0
	v_mov_b32_e32 v70, 0
	v_mov_b32_e32 v71, 0
	v_mov_b32_e32 v84, 0
	v_mov_b32_e32 v85, 0
	v_mov_b32_e32 v82, 0
	v_mov_b32_e32 v83, 0
	s_waitcnt vmcnt(7)
	v_mov_b32_e32 v40, v29
	s_waitcnt vmcnt(6)
	v_mov_b32_e32 v41, v25
	v_mov_b32_e32 v44, v31
	v_mov_b32_e32 v45, v27
	v_mov_b32_e32 v38, v28
	v_mov_b32_e32 v39, v24
	v_mov_b32_e32 v42, v30
	v_mov_b32_e32 v43, v26
	s_waitcnt vmcnt(5)
	v_pk_mul_f32 v[46:47], v[22:23], v[22:23]
	v_pk_mul_f32 v[48:49], v[20:21], v[20:21]
	v_pk_mul_f32 v[40:41], v[40:41], v[40:41]
	v_pk_mul_f32 v[44:45], v[44:45], v[44:45]
	v_pk_mov_b32 v[54:55], v[48:49], v[46:47] op_sel:[1,0]
	v_mov_b32_e32 v49, v47
	v_pk_fma_f32 v[38:39], v[38:39], v[38:39], v[40:41]
	v_pk_fma_f32 v[40:41], v[42:43], v[42:43], v[44:45]
	s_waitcnt vmcnt(4)
	v_mul_f32_e32 v50, v17, v17
	v_mul_f32_e32 v52, v19, v19
	v_pk_add_f32 v[42:43], v[54:55], v[48:49]
	v_pk_add_f32 v[38:39], v[38:39], v[40:41]
	v_pk_fma_f32 v[46:47], v[16:17], v[16:17], v[50:51] op_sel_hi:[1,1,0]
	v_pk_fma_f32 v[50:51], v[18:19], v[18:19], v[52:53] op_sel_hi:[1,1,0]
	s_waitcnt vmcnt(3)
	v_mul_f32_e32 v55, v12, v12
	v_mul_f32_e32 v56, v13, v13
	v_pk_add_f32 v[40:41], v[42:43], v[42:43] op_sel:[0,1] op_sel_hi:[1,0]
	v_pk_add_f32 v[38:39], v[38:39], v[38:39] op_sel:[0,1] op_sel_hi:[1,0]
	v_mul_f32_e32 v47, v14, v14
	v_mul_f32_e32 v51, v15, v15
	s_waitcnt vmcnt(2)
	v_pk_mul_f32 v[44:45], v[10:11], v[10:11]
	v_pk_mul_f32 v[48:49], v[8:9], v[8:9]
	v_mov_b32_e32 v41, v56
	v_mov_b32_e32 v39, v55
	v_pk_mov_b32 v[42:43], v[48:49], v[44:45] op_sel:[1,0]
	v_mov_b32_e32 v49, v45
	v_pk_add_f32 v[46:47], v[46:47], v[50:51]
	v_pk_add_f32 v[38:39], v[38:39], v[40:41]
	s_waitcnt vmcnt(0)
	v_mul_f32_e32 v52, v5, v5
	v_mul_f32_e32 v54, v7, v7
	v_pk_add_f32 v[42:43], v[42:43], v[48:49]
	v_pk_add_f32 v[38:39], v[38:39], v[46:47]
	v_mul_f32_e32 v57, v0, v0
	v_mul_f32_e32 v58, v1, v1
	v_mul_f32_e32 v59, v2, v2
	v_mul_f32_e32 v60, v3, v3
	v_pk_fma_f32 v[44:45], v[4:5], v[4:5], v[52:53] op_sel_hi:[1,1,0]
	v_pk_fma_f32 v[52:53], v[6:7], v[6:7], v[54:55] op_sel_hi:[1,1,0]
	v_pk_add_f32 v[42:43], v[42:43], v[42:43] op_sel:[0,1] op_sel_hi:[1,0]
	v_pk_add_f32 v[38:39], v[38:39], v[38:39] op_sel:[0,1] op_sel_hi:[1,0]
	v_mov_b32_e32 v45, v59
	v_mov_b32_e32 v53, v60
	v_mov_b32_e32 v43, v58
	v_mov_b32_e32 v39, v57
	v_pk_add_f32 v[44:45], v[44:45], v[52:53]
	v_pk_add_f32 v[38:39], v[38:39], v[42:43]
	v_mov_b32_e32 v52, 0
	v_pk_add_f32 v[38:39], v[38:39], v[44:45]
	v_mov_b32_e32 v53, 0
	v_add_f32_e32 v38, v38, v39
	ds_bpermute_b32 v39, v86, v38
	v_mov_b32_e32 v50, 0
	v_mov_b32_e32 v51, 0
	v_mov_b32_e32 v56, 0
	v_mov_b32_e32 v57, 0
	s_waitcnt lgkmcnt(0)
	v_add_f32_e32 v38, v38, v39
	ds_bpermute_b32 v39, v87, v38
	v_mov_b32_e32 v54, 0
	v_mov_b32_e32 v55, 0
	v_mov_b32_e32 v60, 0
	v_mov_b32_e32 v58, 0
	s_waitcnt lgkmcnt(0)
	v_add_f32_e32 v38, v38, v39
	ds_bpermute_b32 v39, v88, v38
	v_mov_b32_e32 v59, 0
	s_waitcnt lgkmcnt(0)
	v_add_f32_e32 v46, v38, v39
	ds_bpermute_b32 v47, v89, v46
	ds_read_b128 v[38:41], v92
	ds_read_b128 v[42:45], v92 offset:8192
	s_waitcnt lgkmcnt(2)
	v_add_f32_e32 v46, v46, v47
	ds_bpermute_b32 v47, v90, v46
	s_waitcnt lgkmcnt(0)
	v_add_f32_e32 v46, v46, v47
	ds_bpermute_b32 v47, v91, v46
	s_waitcnt lgkmcnt(0)
	v_add_f32_e32 v46, v46, v47
	v_fmamk_f32 v46, v46, 0x3a000000, v158
	v_mul_f32_e32 v47, 0x4b800000, v46
	v_cmp_gt_f32_e32 vcc, s23, v46
	s_nop 1
	v_cndmask_b32_e32 v46, v46, v47, vcc
	v_rsq_f32_e32 v46, v46
	s_nop 0
	v_mul_f32_e32 v47, 0x45800000, v46
	v_cndmask_b32_e32 v66, v46, v47, vcc
	v_pk_mul_f32 v[28:29], v[28:29], v[66:67] op_sel_hi:[1,0]
	v_pk_mul_f32 v[30:31], v[30:31], v[66:67] op_sel_hi:[1,0]
	v_pk_fma_f32 v[80:81], v[38:39], v[28:29], v[42:43]
	v_pk_fma_f32 v[78:79], v[40:41], v[30:31], v[44:45]
	v_cvt_pk_bf16_f32 v42, v80, v81
	v_pk_mul_f32 v[24:25], v[24:25], v[66:67] op_sel_hi:[1,0]
	v_cvt_pk_bf16_f32 v43, v78, v79
	ds_read_b128 v[28:31], v92 offset:1024
	ds_read_b128 v[38:41], v92 offset:9216
	v_pk_mul_f32 v[26:27], v[26:27], v[66:67] op_sel_hi:[1,0]
	global_store_dwordx2 v[68:69], v[42:43], off
	v_pk_mul_f32 v[20:21], v[20:21], v[66:67] op_sel_hi:[1,0]
	v_pk_mul_f32 v[22:23], v[22:23], v[66:67] op_sel_hi:[1,0]
	s_waitcnt lgkmcnt(0)
	v_pk_fma_f32 v[72:73], v[30:31], v[26:27], v[40:41]
	v_pk_fma_f32 v[76:77], v[28:29], v[24:25], v[38:39]
	v_pk_mul_f32 v[16:17], v[16:17], v[66:67] op_sel_hi:[1,0]
	v_cvt_pk_bf16_f32 v38, v76, v77
	v_cvt_pk_bf16_f32 v39, v72, v73
	ds_read_b128 v[24:27], v92 offset:2048
	ds_read_b128 v[28:31], v92 offset:10240
	global_store_dwordx2 v[68:69], v[38:39], off offset:512
	v_pk_mul_f32 v[18:19], v[18:19], v[66:67] op_sel_hi:[1,0]
	v_pk_mul_f32 v[12:13], v[12:13], v[66:67] op_sel_hi:[1,0]
	v_pk_mul_f32 v[14:15], v[14:15], v[66:67] op_sel_hi:[1,0]
	s_waitcnt lgkmcnt(0)
; #define LAS __attribute__((address_space(3)))
; __device__ __forceinline__ unsigned cvt_pk_bf16(float lo, float hi) { unsigned r; asm volatile("v_cvt_pk_bf16_f32 %0, %1, %2" : "=v"(r) : "v"(lo), "v"(hi)); return r; }
; template <bool POST, bool PRE>
; __device__ __forceinline__ void row_core(const Params& P, const RowCfg& c, LAS float* vA, LAS float* vB, LAS float* vP, const bf16_t* RAW, const float* SSQ, bf16_t* H, int row, int lane, f32x4 (&v)[8]) {
;     const f32x4* xs = (const f32x4*)(c.xsrc + (size_t)row * DM) + lane;
; #pragma unroll
;     for (int j = 0; j < 8; ++j) v[j] = xs[64 * j];
;     ...
;         for (int j = 0; j < 8; ++j) { const f32x4 a = *(const LAS f32x4*)(vA + j * 256 + lane * 4), b = *(const LAS f32x4*)(vB + j * 256 + lane * 4);
;             v[j] = v[j] * rstd2 * a + b; u32x2 w; w.x = cvt_pk_bf16(v[j][0], v[j][1]); w.y = cvt_pk_bf16(v[j][2], v[j][3]); hs[64 * j] = w; }
; template <bool POST, bool PRE, bool THIN>
; __device__ __forceinline__ void row_phase(const Ctx& F, const RowCfg c) {
;     ...
;             row_core<POST, PRE>(P, c, vA, vB, vP, RAW, SSQ, H, row, lane, v0);
;             if (hasB) row_core<POST, PRE>(P, c, vA, vB, vP, RAW, SSQ, H, rowB, lane, v1);
	v_pk_fma_f32 v[46:47], v[26:27], v[22:23], v[30:31]
	v_pk_fma_f32 v[48:49], v[24:25], v[20:21], v[28:29]
	v_pk_mul_f32 v[8:9], v[8:9], v[66:67] op_sel_hi:[1,0]
	v_cvt_pk_bf16_f32 v28, v48, v49
	v_cvt_pk_bf16_f32 v29, v46, v47
	ds_read_b128 v[20:23], v92 offset:3072
	ds_read_b128 v[24:27], v92 offset:11264
	global_store_dwordx2 v[68:69], v[28:29], off offset:1024
	v_pk_mul_f32 v[10:11], v[10:11], v[66:67] op_sel_hi:[1,0]
	v_pk_mul_f32 v[4:5], v[4:5], v[66:67] op_sel_hi:[1,0]
	v_pk_mul_f32 v[6:7], v[6:7], v[66:67] op_sel_hi:[1,0]
	s_waitcnt lgkmcnt(0)
	v_pk_fma_f32 v[42:43], v[18:19], v[22:23], v[26:27]
	v_pk_fma_f32 v[44:45], v[16:17], v[20:21], v[24:25]
	v_pk_mul_f32 v[0:1], v[0:1], v[66:67] op_sel_hi:[1,0]
	v_cvt_pk_bf16_f32 v24, v44, v45
	v_cvt_pk_bf16_f32 v25, v42, v43
	ds_read_b128 v[16:19], v92 offset:4096
	ds_read_b128 v[20:23], v92 offset:12288
	global_store_dwordx2 v[68:69], v[24:25], off offset:1536
	v_pk_mul_f32 v[2:3], v[2:3], v[66:67] op_sel_hi:[1,0]
	v_mov_b32_e32 v66, 0
	v_mov_b32_e32 v67, 0
	s_waitcnt lgkmcnt(0)
	v_pk_fma_f32 v[38:39], v[14:15], v[18:19], v[22:23]
	v_pk_fma_f32 v[40:41], v[12:13], v[16:17], v[20:21]
	v_mov_b32_e32 v16, 0
	v_cvt_pk_bf16_f32 v22, v40, v41
	v_cvt_pk_bf16_f32 v23, v38, v39
	ds_read_b128 v[12:15], v92 offset:5120
	ds_read_b128 v[18:21], v92 offset:13312
	global_store_dwordx2 v[68:69], v[22:23], off offset:2048
	v_mov_b32_e32 v17, 0
	s_waitcnt lgkmcnt(0)
	v_pk_fma_f32 v[28:29], v[10:11], v[14:15], v[20:21]
	v_pk_fma_f32 v[30:31], v[8:9], v[12:13], v[18:19]
	s_nop 0
	v_cvt_pk_bf16_f32 v18, v30, v31
	v_cvt_pk_bf16_f32 v19, v28, v29
	ds_read_b128 v[8:11], v92 offset:6144
	ds_read_b128 v[12:15], v92 offset:14336
	global_store_dwordx2 v[68:69], v[18:19], off offset:2560
	v_mov_b32_e32 v18, 0
	v_mov_b32_e32 v19, 0
	s_waitcnt lgkmcnt(0)
	v_pk_fma_f32 v[24:25], v[6:7], v[10:11], v[14:15]
	v_pk_fma_f32 v[26:27], v[4:5], v[8:9], v[12:13]
	s_nop 0
	v_cvt_pk_bf16_f32 v12, v26, v27
	v_cvt_pk_bf16_f32 v13, v24, v25
	ds_read_b128 v[4:7], v92 offset:7168
	ds_read_b128 v[8:11], v92 offset:15360
	global_store_dwordx2 v[68:69], v[12:13], off offset:3072
	s_waitcnt lgkmcnt(0)
	v_pk_fma_f32 v[20:21], v[2:3], v[6:7], v[10:11]
	v_pk_fma_f32 v[22:23], v[0:1], v[4:5], v[8:9]
	s_nop 0
	v_cvt_pk_bf16_f32 v0, v22, v23
	v_cvt_pk_bf16_f32 v1, v20, v21
	global_store_dwordx2 v[68:69], v[0:1], off offset:3584
	v_mov_b32_e32 v68, 0
	v_mov_b32_e32 v69, 0
	s_cbranch_scc1 .LBB0_186
	s_ashr_i32 s17, s16, 31
	s_lshl_b64 s[20:21], s[16:17], 13
	v_lshl_add_u64 v[0:1], v[32:33], 0, s[20:21]
	global_load_dwordx4 v[50:53], v[0:1], off nt
	global_load_dwordx4 v[54:57], v[0:1], off offset:1024 nt
	global_load_dwordx4 v[58:61], v[0:1], off offset:2048 nt
	global_load_dwordx4 v[16:19], v[0:1], off offset:3072 nt
	v_add_co_u32_e32 v0, vcc, 0x1000, v0
	s_lshl_b64 s[20:21], s[16:17], 12
	s_nop 0
	v_addc_co_u32_e32 v1, vcc, 0, v1, vcc
	global_load_dwordx4 v[12:15], v[0:1], off nt
	global_load_dwordx4 v[8:11], v[0:1], off offset:1024 nt
	global_load_dwordx4 v[4:7], v[0:1], off offset:2048 nt
	s_nop 0
	global_load_dwordx4 v[0:3], v[0:1], off offset:3072 nt
	v_lshl_add_u64 v[162:163], v[34:35], 0, s[20:21]
	s_waitcnt vmcnt(7)
	v_mov_b32_e32 v64, v51
	s_waitcnt vmcnt(6)
	v_mov_b32_e32 v65, v55
	v_mov_b32_e32 v62, v50
	v_mov_b32_e32 v63, v54
	v_pk_mul_f32 v[64:65], v[64:65], v[64:65]
	v_mov_b32_e32 v66, v53
	v_mov_b32_e32 v67, v57
	v_pk_fma_f32 v[62:63], v[62:63], v[62:63], v[64:65]
	v_mov_b32_e32 v64, v52
	v_mov_b32_e32 v65, v56
	v_pk_mul_f32 v[66:67], v[66:67], v[66:67]
	s_nop 0
	v_pk_fma_f32 v[64:65], v[64:65], v[64:65], v[66:67]
	s_waitcnt vmcnt(5)
	v_pk_mul_f32 v[66:67], v[58:59], v[58:59]
	v_pk_add_f32 v[62:63], v[62:63], v[64:65]
	v_pk_mul_f32 v[64:65], v[60:61], v[60:61]
	v_pk_add_f32 v[62:63], v[62:63], v[62:63] op_sel:[0,1] op_sel_hi:[1,0]
	v_pk_mov_b32 v[68:69], v[66:67], v[64:65] op_sel:[1,0]
	v_mov_b32_e32 v67, v65
	v_pk_add_f32 v[64:65], v[68:69], v[66:67]
	s_waitcnt vmcnt(3)
	v_mul_f32_e32 v66, v12, v12
	v_mul_f32_e32 v67, v13, v13
	v_pk_add_f32 v[64:65], v[64:65], v[64:65] op_sel:[0,1] op_sel_hi:[1,0]
	v_mov_b32_e32 v63, v66
	v_mov_b32_e32 v65, v67
	v_pk_add_f32 v[62:63], v[62:63], v[64:65]
	v_mul_f32_e32 v64, v17, v17
	v_mul_f32_e32 v66, v19, v19
	v_mul_f32_e32 v68, v14, v14
	v_mul_f32_e32 v69, v15, v15
	v_pk_fma_f32 v[64:65], v[16:17], v[16:17], v[64:65] op_sel_hi:[1,1,0]
	v_pk_fma_f32 v[66:67], v[18:19], v[18:19], v[66:67] op_sel_hi:[1,1,0]
	v_mov_b32_e32 v65, v68
	v_mov_b32_e32 v67, v69
	v_pk_add_f32 v[64:65], v[64:65], v[66:67]
	s_waitcnt vmcnt(2)
	v_pk_mul_f32 v[66:67], v[8:9], v[8:9]
	v_pk_add_f32 v[62:63], v[62:63], v[64:65]
	v_pk_mul_f32 v[64:65], v[10:11], v[10:11]
	v_pk_add_f32 v[62:63], v[62:63], v[62:63] op_sel:[0,1] op_sel_hi:[1,0]
	v_pk_mov_b32 v[68:69], v[66:67], v[64:65] op_sel:[1,0]
	v_mov_b32_e32 v67, v65
	v_pk_add_f32 v[64:65], v[68:69], v[66:67]
	s_waitcnt vmcnt(0)
; #define LAS __attribute__((address_space(3)))
; __device__ __forceinline__ unsigned cvt_pk_bf16(float lo, float hi) { unsigned r; asm volatile("v_cvt_pk_bf16_f32 %0, %1, %2" : "=v"(r) : "v"(lo), "v"(hi)); return r; }
; template <bool POST, bool PRE>
; __device__ __forceinline__ void row_core(const Params& P, const RowCfg& c, LAS float* vA, LAS float* vB, LAS float* vP, const bf16_t* RAW, const float* SSQ, bf16_t* H, int row, int lane, f32x4 (&v)[8]) {
;     ...
;         float s2 = 0.f;
; #pragma unroll
;         for (int j = 0; j < 8; ++j) s2 += (v[j][0] * v[j][0] + v[j][1] * v[j][1]) + (v[j][2] * v[j][2] + v[j][3] * v[j][3]);
;         s2 = wave_sum(s2);
;         const float rstd2 = rsqrtf(s2 * (1.0f / DM) + EPS);
;         u32x2* hs = (u32x2*)(H + (size_t)row * DM) + lane;
; #pragma unroll
;         for (int j = 0; j < 8; ++j) { const f32x4 a = *(const LAS f32x4*)(vA + j * 256 + lane * 4), b = *(const LAS f32x4*)(vB + j * 256 + lane * 4);
;             v[j] = v[j] * rstd2 * a + b; u32x2 w; w.x = cvt_pk_bf16(v[j][0], v[j][1]); w.y = cvt_pk_bf16(v[j][2], v[j][3]); hs[64 * j] = w; }
	v_mul_f32_e32 v66, v0, v0
	v_mul_f32_e32 v67, v1, v1
	v_pk_add_f32 v[64:65], v[64:65], v[64:65] op_sel:[0,1] op_sel_hi:[1,0]
	v_mov_b32_e32 v63, v66
	v_mov_b32_e32 v65, v67
	v_pk_add_f32 v[62:63], v[62:63], v[64:65]
	v_mul_f32_e32 v64, v5, v5
	v_mul_f32_e32 v66, v7, v7
	v_mul_f32_e32 v68, v2, v2
	v_mul_f32_e32 v69, v3, v3
	v_pk_fma_f32 v[64:65], v[4:5], v[4:5], v[64:65] op_sel_hi:[1,1,0]
	v_pk_fma_f32 v[66:67], v[6:7], v[6:7], v[66:67] op_sel_hi:[1,1,0]
	v_mov_b32_e32 v65, v68
	v_mov_b32_e32 v67, v69
	v_pk_add_f32 v[64:65], v[64:65], v[66:67]
	s_nop 0
	v_pk_add_f32 v[62:63], v[62:63], v[64:65]
	s_nop 0
	v_add_f32_e32 v62, v62, v63
	ds_bpermute_b32 v63, v86, v62
	s_waitcnt lgkmcnt(0)
	v_add_f32_e32 v62, v62, v63
	ds_bpermute_b32 v63, v87, v62
	s_waitcnt lgkmcnt(0)
	v_add_f32_e32 v62, v62, v63
	ds_bpermute_b32 v63, v88, v62
	s_waitcnt lgkmcnt(0)
	v_add_f32_e32 v62, v62, v63
	ds_bpermute_b32 v63, v89, v62
	s_waitcnt lgkmcnt(0)
	v_add_f32_e32 v62, v62, v63
	ds_bpermute_b32 v63, v90, v62
	s_waitcnt lgkmcnt(0)
	v_add_f32_e32 v62, v62, v63
	ds_bpermute_b32 v63, v91, v62
	s_waitcnt lgkmcnt(0)
	v_add_f32_e32 v62, v62, v63
	v_fmamk_f32 v62, v62, 0x3a000000, v158
	v_cmp_gt_f32_e32 vcc, s23, v62
	v_mul_f32_e32 v63, 0x4b800000, v62
	s_nop 0
	v_cndmask_b32_e32 v62, v62, v63, vcc
	v_rsq_f32_e32 v62, v62
	s_nop 0
	v_mul_f32_e32 v63, 0x45800000, v62
	v_cndmask_b32_e32 v160, v62, v63, vcc
	ds_read_b128 v[62:65], v92
	ds_read_b128 v[66:69], v92 offset:8192
	v_pk_mul_f32 v[50:51], v[50:51], v[160:161] op_sel_hi:[1,0]
	v_pk_mul_f32 v[52:53], v[52:53], v[160:161] op_sel_hi:[1,0]
	v_pk_mul_f32 v[54:55], v[54:55], v[160:161] op_sel_hi:[1,0]
	v_pk_mul_f32 v[56:57], v[56:57], v[160:161] op_sel_hi:[1,0]
	s_waitcnt lgkmcnt(0)
	v_pk_fma_f32 v[82:83], v[64:65], v[52:53], v[68:69]
	v_pk_fma_f32 v[84:85], v[62:63], v[50:51], v[66:67]
	v_pk_mul_f32 v[58:59], v[58:59], v[160:161] op_sel_hi:[1,0]
	v_cvt_pk_bf16_f32 v50, v84, v85
	v_cvt_pk_bf16_f32 v51, v82, v83
	global_store_dwordx2 v[162:163], v[50:51], off
	ds_read_b128 v[50:53], v92 offset:1024
	ds_read_b128 v[62:65], v92 offset:9216
	v_pk_mul_f32 v[60:61], v[60:61], v[160:161] op_sel_hi:[1,0]
	v_pk_mul_f32 v[16:17], v[16:17], v[160:161] op_sel_hi:[1,0]
	v_pk_mul_f32 v[18:19], v[18:19], v[160:161] op_sel_hi:[1,0]
	v_pk_mul_f32 v[12:13], v[12:13], v[160:161] op_sel_hi:[1,0]
	s_waitcnt lgkmcnt(0)
	v_pk_fma_f32 v[70:71], v[52:53], v[56:57], v[64:65]
	v_pk_fma_f32 v[74:75], v[50:51], v[54:55], v[62:63]
	v_pk_mul_f32 v[14:15], v[14:15], v[160:161] op_sel_hi:[1,0]
	v_cvt_pk_bf16_f32 v50, v74, v75
	v_cvt_pk_bf16_f32 v51, v70, v71
	global_store_dwordx2 v[162:163], v[50:51], off offset:512
	ds_read_b128 v[50:53], v92 offset:2048
	ds_read_b128 v[54:57], v92 offset:10240
	v_pk_mul_f32 v[8:9], v[8:9], v[160:161] op_sel_hi:[1,0]
	v_pk_mul_f32 v[10:11], v[10:11], v[160:161] op_sel_hi:[1,0]
	v_pk_mul_f32 v[4:5], v[4:5], v[160:161] op_sel_hi:[1,0]
	v_pk_mul_f32 v[6:7], v[6:7], v[160:161] op_sel_hi:[1,0]
	s_waitcnt lgkmcnt(0)
	v_pk_fma_f32 v[66:67], v[52:53], v[60:61], v[56:57]
	v_pk_fma_f32 v[68:69], v[50:51], v[58:59], v[54:55]
	v_pk_mul_f32 v[0:1], v[0:1], v[160:161] op_sel_hi:[1,0]
	v_cvt_pk_bf16_f32 v50, v68, v69
	v_cvt_pk_bf16_f32 v51, v66, v67
	global_store_dwordx2 v[162:163], v[50:51], off offset:1024
	ds_read_b128 v[50:53], v92 offset:3072
	ds_read_b128 v[54:57], v92 offset:11264
	v_pk_mul_f32 v[2:3], v[2:3], v[160:161] op_sel_hi:[1,0]
	s_waitcnt lgkmcnt(0)
	v_pk_fma_f32 v[18:19], v[18:19], v[52:53], v[56:57]
	v_pk_fma_f32 v[16:17], v[16:17], v[50:51], v[54:55]
	s_nop 0
	v_cvt_pk_bf16_f32 v50, v16, v17
	v_cvt_pk_bf16_f32 v51, v18, v19
	global_store_dwordx2 v[162:163], v[50:51], off offset:1536
	ds_read_b128 v[50:53], v92 offset:4096
	ds_read_b128 v[54:57], v92 offset:12288
	s_waitcnt lgkmcnt(0)
	v_pk_fma_f32 v[64:65], v[14:15], v[52:53], v[56:57]
	v_pk_fma_f32 v[62:63], v[12:13], v[50:51], v[54:55]
	s_nop 0
	v_cvt_pk_bf16_f32 v12, v62, v63
	v_cvt_pk_bf16_f32 v13, v64, v65
	global_store_dwordx2 v[162:163], v[12:13], off offset:2048
	ds_read_b128 v[12:15], v92 offset:5120
	ds_read_b128 v[50:53], v92 offset:13312
	s_waitcnt lgkmcnt(0)
	v_pk_fma_f32 v[58:59], v[10:11], v[14:15], v[52:53]
	v_pk_fma_f32 v[60:61], v[8:9], v[12:13], v[50:51]
	s_nop 0
	v_cvt_pk_bf16_f32 v8, v60, v61
	v_cvt_pk_bf16_f32 v9, v58, v59
	global_store_dwordx2 v[162:163], v[8:9], off offset:2560
	ds_read_b128 v[8:11], v92 offset:6144
	ds_read_b128 v[12:15], v92 offset:14336
	s_waitcnt lgkmcnt(0)
	v_pk_fma_f32 v[54:55], v[6:7], v[10:11], v[14:15]
	v_pk_fma_f32 v[56:57], v[4:5], v[8:9], v[12:13]
	s_nop 0
	v_cvt_pk_bf16_f32 v4, v56, v57
	v_cvt_pk_bf16_f32 v5, v54, v55
	global_store_dwordx2 v[162:163], v[4:5], off offset:3072
	ds_read_b128 v[4:7], v92 offset:7168
	ds_read_b128 v[8:11], v92 offset:15360
	s_waitcnt lgkmcnt(0)
	v_pk_fma_f32 v[50:51], v[2:3], v[6:7], v[10:11]
	v_pk_fma_f32 v[52:53], v[0:1], v[4:5], v[8:9]
	s_nop 0
	v_cvt_pk_bf16_f32 v0, v52, v53
	v_cvt_pk_bf16_f32 v1, v50, v51
	global_store_dwordx2 v[162:163], v[0:1], off offset:3584

; #define LAS __attribute__((address_space(3)))
; template <bool POST, bool PRE>
; __device__ __forceinline__ void row_core(const Params& P, const RowCfg& c, LAS float* vA, LAS float* vB, LAS float* vP, const bf16_t* RAW, const float* SSQ, bf16_t* H, int row, int lane, f32x4 (&v)[8]) {
;     ...
;         const u32x2* rs = (const u32x2*)(RAW + (size_t)row * DM) + lane;
;         float s = (lane < 32) ? SSQ[(size_t)row * 32 + lane] : 0.f; s = wave_sum(s);
;         const float rstd = rsqrtf(s * (1.0f / DM) + EPS);
;         f32x4* os = (f32x4*)(P.out + (size_t)row * DM) + lane;
; #pragma unroll
;         for (int j = 0; j < 8; ++j) { const u32x2 rb = rs[64 * j]; const f32x4 r = (f32x4){__uint_as_float(rb.x << 16), __uint_as_float(rb.x & 0xffff0000u), __uint_as_float(rb.y << 16), __uint_as_float(rb.y & 0xffff0000u)};
;             const f32x4 pv = *(const LAS f32x4*)(vP + j * 256 + lane * 4); v[j] += r * rstd * pv; os[64 * j] = v[j]; }
.LBB0_1273:
	s_or_b64 exec, exec, s[20:21]
	v_lshl_add_u64 v[38:39], s[92:93], 0, v[36:37]
	v_add_co_u32_e32 v44, vcc, s9, v38
	s_waitcnt vmcnt(0)
	ds_bpermute_b32 v41, v43, v40
	v_addc_co_u32_e32 v45, vcc, 0, v39, vcc
	global_load_dwordx2 v[62:63], v[44:45], off
	s_add_i32 s6, s6, s8
	s_waitcnt lgkmcnt(0)
	v_add_f32_e32 v40, v40, v41
	ds_bpermute_b32 v41, v46, v40
	s_add_u32 s12, s12, s14
	s_addc_u32 s13, s13, s15
	v_lshl_add_u64 v[34:35], v[34:35], 0, s[10:11]
	v_lshl_add_u64 v[36:37], v[36:37], 0, s[16:17]
	s_waitcnt lgkmcnt(0)
	v_add_f32_e32 v40, v40, v41
	ds_bpermute_b32 v41, v47, v40
	s_waitcnt lgkmcnt(0)
	v_add_f32_e32 v40, v40, v41
	ds_bpermute_b32 v41, v48, v40
	s_waitcnt lgkmcnt(0)
	v_add_f32_e32 v40, v40, v41
	ds_bpermute_b32 v41, v49, v40
	s_waitcnt lgkmcnt(0)
	v_add_f32_e32 v42, v40, v41
	ds_bpermute_b32 v52, v50, v42
	v_lshl_add_u64 v[40:41], s[18:19], 0, v[32:33]
	s_add_u32 s18, s18, s14
	s_addc_u32 s19, s19, s15
	s_cmpk_lt_i32 s6, 0x4000
	s_waitcnt lgkmcnt(0)
	v_add_f32_e32 v42, v42, v52
	v_fmamk_f32 v42, v42, 0x3a000000, v51
	v_mul_f32_e32 v52, 0x4b800000, v42
	v_cmp_gt_f32_e32 vcc, s7, v42
	s_waitcnt vmcnt(0)
	v_lshlrev_b32_e32 v64, 16, v62
	v_cndmask_b32_e32 v42, v42, v52, vcc
	v_rsq_f32_e32 v42, v42
	v_add_u32_e32 v52, 0, v32
	ds_read_b128 v[54:57], v52 offset:16384
	ds_read_b128 v[58:61], v52 offset:17408
	v_and_b32_e32 v65, 0xffff0000, v62
	v_mul_f32_e32 v53, 0x45800000, v42
	v_cndmask_b32_e32 v42, v42, v53, vcc
	v_lshlrev_b32_e32 v62, 16, v63
	v_and_b32_e32 v63, 0xffff0000, v63
	v_pk_mul_f32 v[64:65], v[42:43], v[64:65] op_sel_hi:[0,1]
	v_pk_mul_f32 v[62:63], v[42:43], v[62:63] op_sel_hi:[0,1]
	s_waitcnt lgkmcnt(1)
	v_pk_fma_f32 v[2:3], v[56:57], v[62:63], v[2:3]
	v_pk_fma_f32 v[0:1], v[54:55], v[64:65], v[0:1]
	global_store_dwordx4 v[40:41], v[0:3], off nt
	global_load_dwordx2 v[54:55], v[44:45], off offset:512
	s_waitcnt vmcnt(0)
	v_lshlrev_b32_e32 v56, 16, v54
	v_and_b32_e32 v57, 0xffff0000, v54
	v_lshlrev_b32_e32 v54, 16, v55
	v_and_b32_e32 v55, 0xffff0000, v55
	v_pk_mul_f32 v[56:57], v[42:43], v[56:57] op_sel_hi:[0,1]
	v_pk_mul_f32 v[54:55], v[42:43], v[54:55] op_sel_hi:[0,1]
	s_waitcnt lgkmcnt(0)
	v_pk_fma_f32 v[6:7], v[60:61], v[54:55], v[6:7]
	v_pk_fma_f32 v[4:5], v[58:59], v[56:57], v[4:5]
	global_store_dwordx4 v[40:41], v[4:7], off offset:1024 nt
	global_load_dwordx2 v[62:63], v[44:45], off offset:1024
	ds_read_b128 v[54:57], v52 offset:18432
	ds_read_b128 v[58:61], v52 offset:19456
	s_waitcnt vmcnt(0)
	v_lshlrev_b32_e32 v64, 16, v62
	v_and_b32_e32 v65, 0xffff0000, v62
	v_lshlrev_b32_e32 v62, 16, v63
	v_and_b32_e32 v63, 0xffff0000, v63
	v_pk_mul_f32 v[64:65], v[42:43], v[64:65] op_sel_hi:[0,1]
	v_pk_mul_f32 v[62:63], v[42:43], v[62:63] op_sel_hi:[0,1]
	s_waitcnt lgkmcnt(1)
	v_pk_fma_f32 v[10:11], v[56:57], v[62:63], v[10:11]
	v_pk_fma_f32 v[8:9], v[54:55], v[64:65], v[8:9]
	global_store_dwordx4 v[40:41], v[8:11], off offset:2048 nt
	global_load_dwordx2 v[54:55], v[44:45], off offset:1536
	s_waitcnt vmcnt(0)
	v_lshlrev_b32_e32 v56, 16, v54
	v_and_b32_e32 v57, 0xffff0000, v54
	v_lshlrev_b32_e32 v54, 16, v55
	v_and_b32_e32 v55, 0xffff0000, v55
	v_pk_mul_f32 v[56:57], v[42:43], v[56:57] op_sel_hi:[0,1]
	v_pk_mul_f32 v[54:55], v[42:43], v[54:55] op_sel_hi:[0,1]
	s_waitcnt lgkmcnt(0)
	v_pk_fma_f32 v[14:15], v[60:61], v[54:55], v[14:15]
	v_pk_fma_f32 v[12:13], v[58:59], v[56:57], v[12:13]
	global_store_dwordx4 v[40:41], v[12:15], off offset:3072 nt
	global_load_dwordx2 v[62:63], v[44:45], off offset:2048
	ds_read_b128 v[54:57], v52 offset:20480
	ds_read_b128 v[58:61], v52 offset:21504
	v_add_co_u32_e32 v40, vcc, s3, v40
	s_waitcnt vmcnt(0)
	v_lshlrev_b32_e32 v64, 16, v62
	v_and_b32_e32 v65, 0xffff0000, v62
	v_lshlrev_b32_e32 v62, 16, v63
	v_and_b32_e32 v63, 0xffff0000, v63
	v_pk_mul_f32 v[64:65], v[42:43], v[64:65] op_sel_hi:[0,1]
	v_pk_mul_f32 v[62:63], v[42:43], v[62:63] op_sel_hi:[0,1]
	v_addc_co_u32_e32 v41, vcc, 0, v41, vcc
	s_waitcnt lgkmcnt(1)
	v_pk_fma_f32 v[18:19], v[56:57], v[62:63], v[18:19]
	v_pk_fma_f32 v[16:17], v[54:55], v[64:65], v[16:17]
	global_store_dwordx4 v[40:41], v[16:19], off nt
	global_load_dwordx2 v[54:55], v[44:45], off offset:2560
	s_waitcnt vmcnt(0)
	v_lshlrev_b32_e32 v56, 16, v54
	v_and_b32_e32 v57, 0xffff0000, v54
	v_lshlrev_b32_e32 v54, 16, v55
	v_and_b32_e32 v55, 0xffff0000, v55
	v_pk_mul_f32 v[56:57], v[42:43], v[56:57] op_sel_hi:[0,1]
	v_pk_mul_f32 v[54:55], v[42:43], v[54:55] op_sel_hi:[0,1]
	s_waitcnt lgkmcnt(0)
	v_pk_fma_f32 v[22:23], v[60:61], v[54:55], v[22:23]
	v_pk_fma_f32 v[20:21], v[58:59], v[56:57], v[20:21]
	global_store_dwordx4 v[40:41], v[20:23], off offset:1024 nt
	global_load_dwordx2 v[62:63], v[44:45], off offset:3072
	ds_read_b128 v[54:57], v52 offset:22528
	ds_read_b128 v[58:61], v52 offset:23552
	s_waitcnt vmcnt(0)
	v_lshlrev_b32_e32 v64, 16, v62
	v_and_b32_e32 v65, 0xffff0000, v62
	v_lshlrev_b32_e32 v62, 16, v63
	v_and_b32_e32 v63, 0xffff0000, v63
	v_pk_mul_f32 v[64:65], v[42:43], v[64:65] op_sel_hi:[0,1]
	v_pk_mul_f32 v[62:63], v[42:43], v[62:63] op_sel_hi:[0,1]
	s_waitcnt lgkmcnt(1)
; #define LAS __attribute__((address_space(3)))
; __device__ __forceinline__ unsigned cvt_pk_bf16(float lo, float hi) { unsigned r; asm volatile("v_cvt_pk_bf16_f32 %0, %1, %2" : "=v"(r) : "v"(lo), "v"(hi)); return r; }
; template <bool POST, bool PRE>
; __device__ __forceinline__ void row_core(const Params& P, const RowCfg& c, LAS float* vA, LAS float* vB, LAS float* vP, const bf16_t* RAW, const float* SSQ, bf16_t* H, int row, int lane, f32x4 (&v)[8]) {
;     ...
;             const f32x4 pv = *(const LAS f32x4*)(vP + j * 256 + lane * 4); v[j] += r * rstd * pv; os[64 * j] = v[j]; }
;     ...
;         float s2 = 0.f;
; #pragma unroll
;         for (int j = 0; j < 8; ++j) s2 += (v[j][0] * v[j][0] + v[j][1] * v[j][1]) + (v[j][2] * v[j][2] + v[j][3] * v[j][3]);
;         s2 = wave_sum(s2);
;         const float rstd2 = rsqrtf(s2 * (1.0f / DM) + EPS);
;         u32x2* hs = (u32x2*)(H + (size_t)row * DM) + lane;
; #pragma unroll
;         for (int j = 0; j < 8; ++j) { const f32x4 a = *(const LAS f32x4*)(vA + j * 256 + lane * 4), b = *(const LAS f32x4*)(vB + j * 256 + lane * 4);
;             v[j] = v[j] * rstd2 * a + b; u32x2 w; w.x = cvt_pk_bf16(v[j][0], v[j][1]); w.y = cvt_pk_bf16(v[j][2], v[j][3]); hs[64 * j] = w; }
	v_pk_fma_f32 v[30:31], v[56:57], v[62:63], v[30:31]
	v_pk_fma_f32 v[28:29], v[54:55], v[64:65], v[28:29]
	global_store_dwordx4 v[40:41], v[28:31], off offset:2048 nt
	global_load_dwordx2 v[44:45], v[44:45], off offset:3584
	v_mov_b32_e32 v56, v1
	v_mov_b32_e32 v64, v3
	v_mov_b32_e32 v57, v5
	v_mov_b32_e32 v65, v7
	v_mov_b32_e32 v54, v0
	v_mov_b32_e32 v62, v2
	v_mov_b32_e32 v55, v4
	v_mov_b32_e32 v63, v6
	v_pk_mul_f32 v[56:57], v[56:57], v[56:57]
	v_pk_mul_f32 v[64:65], v[64:65], v[64:65]
	v_pk_fma_f32 v[54:55], v[54:55], v[54:55], v[56:57]
	v_pk_fma_f32 v[56:57], v[62:63], v[62:63], v[64:65]
	v_pk_mul_f32 v[62:63], v[8:9], v[8:9]
	v_pk_add_f32 v[54:55], v[54:55], v[56:57]
	v_pk_mul_f32 v[56:57], v[10:11], v[10:11]
	v_pk_add_f32 v[54:55], v[54:55], v[54:55] op_sel:[0,1] op_sel_hi:[1,0]
	v_pk_mov_b32 v[64:65], v[62:63], v[56:57] op_sel:[1,0]
	v_mov_b32_e32 v63, v57
	v_pk_add_f32 v[56:57], v[64:65], v[62:63]
	v_mul_f32_e32 v62, v13, v13
	v_mul_f32_e32 v64, v15, v15
	v_pk_add_f32 v[56:57], v[56:57], v[56:57] op_sel:[0,1] op_sel_hi:[1,0]
	v_pk_fma_f32 v[62:63], v[12:13], v[12:13], v[62:63] op_sel_hi:[1,1,0]
	v_pk_fma_f32 v[64:65], v[14:15], v[14:15], v[64:65] op_sel_hi:[1,1,0]
	v_mul_f32_e32 v55, v16, v16
	v_mul_f32_e32 v57, v17, v17
	v_mul_f32_e32 v63, v18, v18
	v_mul_f32_e32 v65, v19, v19
	v_pk_add_f32 v[54:55], v[54:55], v[56:57]
	v_pk_add_f32 v[56:57], v[62:63], v[64:65]
	v_pk_mul_f32 v[62:63], v[20:21], v[20:21]
	v_pk_add_f32 v[54:55], v[54:55], v[56:57]
	v_pk_mul_f32 v[56:57], v[22:23], v[22:23]
	v_pk_add_f32 v[54:55], v[54:55], v[54:55] op_sel:[0,1] op_sel_hi:[1,0]
	v_pk_mov_b32 v[64:65], v[62:63], v[56:57] op_sel:[1,0]
	v_mov_b32_e32 v63, v57
	v_pk_add_f32 v[56:57], v[64:65], v[62:63]
	v_mul_f32_e32 v62, v29, v29
	v_mul_f32_e32 v64, v31, v31
	v_pk_add_f32 v[56:57], v[56:57], v[56:57] op_sel:[0,1] op_sel_hi:[1,0]
	v_pk_fma_f32 v[62:63], v[28:29], v[28:29], v[62:63] op_sel_hi:[1,1,0]
	v_pk_fma_f32 v[64:65], v[30:31], v[30:31], v[64:65] op_sel_hi:[1,1,0]
	s_waitcnt vmcnt(0)
	v_lshlrev_b32_e32 v66, 16, v44
	v_and_b32_e32 v67, 0xffff0000, v44
	v_lshlrev_b32_e32 v44, 16, v45
	v_and_b32_e32 v45, 0xffff0000, v45
	v_pk_mul_f32 v[66:67], v[42:43], v[66:67] op_sel_hi:[0,1]
	v_pk_mul_f32 v[44:45], v[42:43], v[44:45] op_sel_hi:[0,1]
	s_waitcnt lgkmcnt(0)
	v_pk_fma_f32 v[26:27], v[60:61], v[44:45], v[26:27]
	v_pk_fma_f32 v[24:25], v[58:59], v[66:67], v[24:25]
	v_mul_f32_e32 v63, v26, v26
	v_mul_f32_e32 v55, v24, v24
	v_mul_f32_e32 v57, v25, v25
	v_mul_f32_e32 v65, v27, v27
	v_pk_add_f32 v[44:45], v[54:55], v[56:57]
	v_pk_add_f32 v[54:55], v[62:63], v[64:65]
	s_nop 0
	v_pk_add_f32 v[44:45], v[44:45], v[54:55]
	ds_read_b128 v[54:57], v52
	ds_read_b128 v[58:61], v52 offset:8192
	v_add_f32_e32 v42, v44, v45
	ds_bpermute_b32 v44, v43, v42
	global_store_dwordx4 v[40:41], v[24:27], off offset:3072 nt
	s_waitcnt lgkmcnt(0)
	v_add_f32_e32 v42, v42, v44
	ds_bpermute_b32 v44, v46, v42
	s_waitcnt lgkmcnt(0)
	v_add_f32_e32 v42, v42, v44
	ds_bpermute_b32 v44, v47, v42
	s_waitcnt lgkmcnt(0)
	v_add_f32_e32 v42, v42, v44
	ds_bpermute_b32 v44, v48, v42
	s_waitcnt lgkmcnt(0)
	v_add_f32_e32 v42, v42, v44
	ds_bpermute_b32 v44, v49, v42
	s_waitcnt lgkmcnt(0)
	v_add_f32_e32 v42, v42, v44
	ds_bpermute_b32 v44, v50, v42
	s_waitcnt lgkmcnt(0)
	v_add_f32_e32 v42, v42, v44
	v_fmamk_f32 v42, v42, 0x3a000000, v51
	v_mul_f32_e32 v44, 0x4b800000, v42
	v_cmp_gt_f32_e32 vcc, s7, v42
	s_nop 1
	v_cndmask_b32_e32 v42, v42, v44, vcc
	v_rsq_f32_e32 v42, v42
	s_nop 0
	v_mul_f32_e32 v40, 0x45800000, v42
	v_cndmask_b32_e32 v40, v42, v40, vcc
	v_pk_mul_f32 v[0:1], v[0:1], v[40:41] op_sel_hi:[1,0]
	v_pk_mul_f32 v[2:3], v[2:3], v[40:41] op_sel_hi:[1,0]
	v_pk_fma_f32 v[0:1], v[54:55], v[0:1], v[58:59]
	v_pk_fma_f32 v[2:3], v[56:57], v[2:3], v[60:61]
	v_cvt_pk_bf16_f32 v44, v0, v1
	v_add_co_u32_e32 v38, vcc, s22, v38
	v_cvt_pk_bf16_f32 v45, v2, v3
	ds_read_b128 v[0:3], v52 offset:1024
	ds_read_b128 v[54:57], v52 offset:9216
	v_pk_mul_f32 v[4:5], v[4:5], v[40:41] op_sel_hi:[1,0]
	v_pk_mul_f32 v[6:7], v[6:7], v[40:41] op_sel_hi:[1,0]
	v_addc_co_u32_e32 v39, vcc, 0, v39, vcc
	s_waitcnt lgkmcnt(0)
	v_pk_fma_f32 v[2:3], v[2:3], v[6:7], v[56:57]
	v_pk_fma_f32 v[0:1], v[0:1], v[4:5], v[54:55]
	global_store_dwordx2 v[38:39], v[44:45], off
	v_cvt_pk_bf16_f32 v44, v0, v1
	v_cvt_pk_bf16_f32 v45, v2, v3
	ds_read_b128 v[0:3], v52 offset:2048
	ds_read_b128 v[4:7], v52 offset:10240
	v_pk_mul_f32 v[8:9], v[8:9], v[40:41] op_sel_hi:[1,0]
	v_pk_mul_f32 v[10:11], v[10:11], v[40:41] op_sel_hi:[1,0]
	global_store_dwordx2 v[38:39], v[44:45], off offset:512
	s_waitcnt lgkmcnt(0)
	v_pk_fma_f32 v[2:3], v[2:3], v[10:11], v[6:7]
	v_pk_fma_f32 v[0:1], v[0:1], v[8:9], v[4:5]
	v_pk_mul_f32 v[10:11], v[12:13], v[40:41] op_sel_hi:[1,0]
	v_cvt_pk_bf16_f32 v8, v0, v1
	v_cvt_pk_bf16_f32 v9, v2, v3
	ds_read_b128 v[0:3], v52 offset:3072
	ds_read_b128 v[4:7], v52 offset:11264
	v_pk_mul_f32 v[12:13], v[14:15], v[40:41] op_sel_hi:[1,0]
	global_store_dwordx2 v[38:39], v[8:9], off offset:1024
	s_waitcnt lgkmcnt(0)
	v_pk_fma_f32 v[2:3], v[2:3], v[12:13], v[6:7]
	v_pk_fma_f32 v[0:1], v[0:1], v[10:11], v[4:5]
	v_pk_mul_f32 v[10:11], v[16:17], v[40:41] op_sel_hi:[1,0]
	v_cvt_pk_bf16_f32 v8, v0, v1
	v_cvt_pk_bf16_f32 v9, v2, v3
	ds_read_b128 v[0:3], v52 offset:4096
	ds_read_b128 v[4:7], v52 offset:12288
	v_pk_mul_f32 v[12:13], v[18:19], v[40:41] op_sel_hi:[1,0]
	global_store_dwordx2 v[38:39], v[8:9], off offset:1536
	s_waitcnt lgkmcnt(0)
	v_pk_fma_f32 v[2:3], v[2:3], v[12:13], v[6:7]
	v_pk_fma_f32 v[0:1], v[0:1], v[10:11], v[4:5]
	v_pk_mul_f32 v[10:11], v[20:21], v[40:41] op_sel_hi:[1,0]
	v_cvt_pk_bf16_f32 v8, v0, v1
	v_cvt_pk_bf16_f32 v9, v2, v3
	ds_read_b128 v[0:3], v52 offset:5120
	ds_read_b128 v[4:7], v52 offset:13312
	v_pk_mul_f32 v[12:13], v[22:23], v[40:41] op_sel_hi:[1,0]
	global_store_dwordx2 v[38:39], v[8:9], off offset:2048
	s_waitcnt lgkmcnt(0)
	v_pk_fma_f32 v[2:3], v[12:13], v[2:3], v[6:7]
	v_pk_fma_f32 v[0:1], v[10:11], v[0:1], v[4:5]
	v_pk_mul_f32 v[10:11], v[28:29], v[40:41] op_sel_hi:[1,0]
	v_cvt_pk_bf16_f32 v8, v0, v1
	v_cvt_pk_bf16_f32 v9, v2, v3
	ds_read_b128 v[0:3], v52 offset:6144
	ds_read_b128 v[4:7], v52 offset:14336
	v_pk_mul_f32 v[12:13], v[30:31], v[40:41] op_sel_hi:[1,0]
	global_store_dwordx2 v[38:39], v[8:9], off offset:2560
	s_waitcnt lgkmcnt(0)
	v_pk_fma_f32 v[2:3], v[12:13], v[2:3], v[6:7]
	v_pk_fma_f32 v[0:1], v[10:11], v[0:1], v[4:5]
	v_pk_mul_f32 v[10:11], v[24:25], v[40:41] op_sel_hi:[1,0]
	v_cvt_pk_bf16_f32 v8, v0, v1
	v_cvt_pk_bf16_f32 v9, v2, v3
	ds_read_b128 v[0:3], v52 offset:7168
	ds_read_b128 v[4:7], v52 offset:15360
	v_pk_mul_f32 v[12:13], v[26:27], v[40:41] op_sel_hi:[1,0]
	global_store_dwordx2 v[38:39], v[8:9], off offset:3072
	s_waitcnt lgkmcnt(0)
	v_pk_fma_f32 v[0:1], v[10:11], v[0:1], v[4:5]
	v_pk_fma_f32 v[2:3], v[12:13], v[2:3], v[6:7]
	v_cvt_pk_bf16_f32 v0, v0, v1
	s_nop 0
	v_cvt_pk_bf16_f32 v1, v2, v3
	global_store_dwordx2 v[38:39], v[0:1], off offset:3584
	s_cbranch_scc0 .LBB0_1276
; template <bool POST, bool PRE>
; __device__ __forceinline__ void row_core(const Params& P, const RowCfg& c, LAS float* vA, LAS float* vB, LAS float* vP, const bf16_t* RAW, const float* SSQ, bf16_t* H, int row, int lane, f32x4 (&v)[8]) {
;     const f32x4* xs = (const f32x4*)(c.xsrc + (size_t)row * DM) + lane;
; #pragma unroll
;     for (int j = 0; j < 8; ++j) v[j] = xs[64 * j];
;     if (POST) {
;         const u32x2* rs = (const u32x2*)(RAW + (size_t)row * DM) + lane;
;         float s = (lane < 32) ? SSQ[(size_t)row * 32 + lane] : 0.f; s = wave_sum(s);
.LBB0_1274:
	v_lshl_add_u64 v[16:17], s[12:13], 0, v[32:33]
	v_add_co_u32_e32 v24, vcc, 0x1000, v16
	global_load_dwordx4 v[0:3], v[16:17], off nt
	global_load_dwordx4 v[4:7], v[16:17], off offset:1024 nt
	global_load_dwordx4 v[8:11], v[16:17], off offset:2048 nt
	global_load_dwordx4 v[12:15], v[16:17], off offset:3072 nt
	v_addc_co_u32_e32 v25, vcc, 0, v17, vcc
	global_load_dwordx4 v[16:19], v[24:25], off nt
	global_load_dwordx4 v[20:23], v[24:25], off offset:1024 nt
	global_load_dwordx4 v[28:31], v[24:25], off offset:2048 nt
	s_nop 0
	global_load_dwordx4 v[24:27], v[24:25], off offset:3072 nt
	v_mov_b32_e32 v40, 0
	s_and_saveexec_b64 s[20:21], s[0:1]
	s_cbranch_execz .LBB0_1273
	v_lshl_add_u64 v[38:39], s[92:93], 0, v[34:35]
	global_load_dword v40, v[38:39], off
	s_branch .LBB0_1273

; #define LAS __attribute__((address_space(3)))
; template <bool POST, bool PRE>
; __device__ __forceinline__ void row_core(const Params& P, const RowCfg& c, LAS float* vA, LAS float* vB, LAS float* vP, const bf16_t* RAW, const float* SSQ, bf16_t* H, int row, int lane, f32x4 (&v)[8]) {
;     const f32x4* xs = (const f32x4*)(c.xsrc + (size_t)row * DM) + lane;
; #pragma unroll
;     for (int j = 0; j < 8; ++j) v[j] = xs[64 * j];
;     if (POST) {
;         const u32x2* rs = (const u32x2*)(RAW + (size_t)row * DM) + lane;
;         float s = (lane < 32) ? SSQ[(size_t)row * 32 + lane] : 0.f; s = wave_sum(s);
;         const float rstd = rsqrtf(s * (1.0f / DM) + EPS);
;         f32x4* os = (f32x4*)(P.out + (size_t)row * DM) + lane;
; #pragma unroll
;         for (int j = 0; j < 8; ++j) { const u32x2 rb = rs[64 * j]; const f32x4 r = (f32x4){__uint_as_float(rb.x << 16), __uint_as_float(rb.x & 0xffff0000u), __uint_as_float(rb.y << 16), __uint_as_float(rb.y & 0xffff0000u)};
;             const f32x4 pv = *(const LAS f32x4*)(vP + j * 256 + lane * 4); v[j] += r * rstd * pv; os[64 * j] = v[j]; }
; template <bool POST, bool PRE, bool THIN>
; __device__ __forceinline__ void row_phase(const Ctx& F, const RowCfg c) {
;     ...
;         for (int row = gw; row < SEQ; row += 2 * NGW) {
;             f32x4 v0[8], v1[8];
;             const int rowB = row + NGW; const bool hasB = rowB < SEQ;
;             row_core<POST, PRE>(P, c, vA, vB, vP, RAW, SSQ, H, row, lane, v0);
.LBB0_1503:
	global_load_dwordx4 v[4:7], v[58:59], off offset:-4096 nt
	global_load_dwordx4 v[8:11], v[58:59], off offset:-3072 nt
	global_load_dwordx4 v[12:15], v[58:59], off offset:-2048 nt
	global_load_dwordx4 v[16:19], v[58:59], off offset:-1024 nt
	global_load_dwordx4 v[20:23], v[58:59], off nt
	global_load_dwordx4 v[24:27], v[58:59], off offset:1024 nt
	global_load_dwordx4 v[28:31], v[58:59], off offset:2048 nt
	s_waitcnt lgkmcnt(0)
	global_load_dwordx4 v[0:3], v[58:59], off offset:3072 nt
	v_mov_b32_e32 v32, 0
	s_and_saveexec_b64 s[38:39], s[0:1]
	s_cbranch_execz .LBB0_1505
	v_lshl_add_u64 v[32:33], s[92:93], 0, v[54:55]
	global_load_dword v32, v[32:33], off
.LBB0_1505:
	s_or_b64 exec, exec, s[38:39]
	v_lshl_add_u64 v[62:63], s[92:93], 0, v[60:61]
	v_add_co_u32_e32 v40, vcc, s19, v62
	s_waitcnt vmcnt(0)
	ds_bpermute_b32 v33, v106, v32
	v_addc_co_u32_e32 v41, vcc, 0, v63, vcc
	global_load_dwordx2 v[42:43], v[40:41], off
	s_add_i32 s38, s3, s16
	s_waitcnt lgkmcnt(0)
	v_add_f32_e32 v32, v32, v33
	ds_bpermute_b32 v33, v107, v32
	s_cmpk_lt_i32 s38, 0x4000
	v_mov_b32_e32 v83, 0
	v_mov_b32_e32 v82, 0
	v_mov_b32_e32 v85, 0
	s_waitcnt lgkmcnt(0)
	v_add_f32_e32 v32, v32, v33
	ds_bpermute_b32 v33, v108, v32
	v_mov_b32_e32 v84, 0
	v_mov_b32_e32 v87, 0
	v_mov_b32_e32 v86, 0
	v_mov_b32_e32 v91, 0
	s_waitcnt lgkmcnt(0)
	v_add_f32_e32 v32, v32, v33
	ds_bpermute_b32 v33, v109, v32
	v_mov_b32_e32 v90, 0
	v_mov_b32_e32 v89, 0
	v_mov_b32_e32 v88, 0
	v_mov_b32_e32 v93, 0
	s_waitcnt lgkmcnt(0)
	v_add_f32_e32 v32, v32, v33
	ds_bpermute_b32 v33, v110, v32
	v_mov_b32_e32 v92, 0
	v_mov_b32_e32 v95, 0
	v_mov_b32_e32 v94, 0
	v_mov_b32_e32 v99, 0
	s_waitcnt lgkmcnt(0)
	v_add_f32_e32 v32, v32, v33
	ds_bpermute_b32 v33, v111, v32
	v_mov_b32_e32 v98, 0
	v_mov_b32_e32 v97, 0
	v_mov_b32_e32 v96, 0
	v_mov_b32_e32 v101, 0
	s_waitcnt lgkmcnt(0)
	v_add_f32_e32 v32, v32, v33
	v_fmamk_f32 v32, v32, 0x3a000000, v178
	v_mul_f32_e32 v33, 0x4b800000, v32
	v_cmp_gt_f32_e32 vcc, s17, v32
	v_mov_b32_e32 v100, 0
	v_mov_b32_e32 v103, 0
	v_cndmask_b32_e32 v32, v32, v33, vcc
	v_rsq_f32_e32 v64, v32
	ds_read_b128 v[32:35], v112 offset:16384
	ds_read_b128 v[36:39], v112 offset:17408
	v_mov_b32_e32 v102, 0
	v_mov_b32_e32 v105, 0
	v_mul_f32_e32 v65, 0x45800000, v64
	v_cndmask_b32_e32 v64, v64, v65, vcc
	v_mov_b32_e32 v104, 0
	s_cselect_b64 s[40:41], -1, 0
	s_cmpk_gt_i32 s38, 0x3fff
	s_waitcnt vmcnt(0)
	v_lshlrev_b32_e32 v66, 16, v42
	v_and_b32_e32 v67, 0xffff0000, v42
	v_lshlrev_b32_e32 v42, 16, v43
	v_and_b32_e32 v43, 0xffff0000, v43
	v_pk_mul_f32 v[66:67], v[64:65], v[66:67] op_sel_hi:[0,1]
	v_pk_mul_f32 v[42:43], v[64:65], v[42:43] op_sel_hi:[0,1]
	s_waitcnt lgkmcnt(1)
	v_pk_fma_f32 v[6:7], v[34:35], v[42:43], v[6:7]
	v_pk_fma_f32 v[4:5], v[32:33], v[66:67], v[4:5]
	global_store_dwordx4 v[58:59], v[4:7], off offset:-4096 nt
	global_load_dwordx2 v[32:33], v[40:41], off offset:512
	v_mov_b32_e32 v70, v5
	v_mov_b32_e32 v74, v7
	v_mov_b32_e32 v68, v4
	v_mov_b32_e32 v72, v6
	s_waitcnt vmcnt(0)
	v_lshlrev_b32_e32 v34, 16, v32
	v_and_b32_e32 v35, 0xffff0000, v32
	v_lshlrev_b32_e32 v32, 16, v33
	v_and_b32_e32 v33, 0xffff0000, v33
	v_pk_mul_f32 v[34:35], v[64:65], v[34:35] op_sel_hi:[0,1]
	v_pk_mul_f32 v[32:33], v[64:65], v[32:33] op_sel_hi:[0,1]
	s_waitcnt lgkmcnt(0)
	v_pk_fma_f32 v[10:11], v[38:39], v[32:33], v[10:11]
	v_pk_fma_f32 v[8:9], v[36:37], v[34:35], v[8:9]
	global_store_dwordx4 v[58:59], v[8:11], off offset:-3072 nt
	global_load_dwordx2 v[42:43], v[40:41], off offset:1024
	ds_read_b128 v[32:35], v112 offset:18432
	ds_read_b128 v[36:39], v112 offset:19456
	v_mov_b32_e32 v71, v9
	v_mov_b32_e32 v75, v11
	v_mov_b32_e32 v69, v8
	v_mov_b32_e32 v73, v10
	v_pk_mul_f32 v[70:71], v[70:71], v[70:71]
	v_pk_mul_f32 v[74:75], v[74:75], v[74:75]
	v_pk_fma_f32 v[68:69], v[68:69], v[68:69], v[70:71]
	v_pk_fma_f32 v[70:71], v[72:73], v[72:73], v[74:75]
	s_waitcnt vmcnt(0)
	v_lshlrev_b32_e32 v66, 16, v42
	v_and_b32_e32 v67, 0xffff0000, v42
	v_lshlrev_b32_e32 v42, 16, v43
	v_and_b32_e32 v43, 0xffff0000, v43
	v_pk_mul_f32 v[66:67], v[64:65], v[66:67] op_sel_hi:[0,1]
	v_pk_mul_f32 v[42:43], v[64:65], v[42:43] op_sel_hi:[0,1]
	s_waitcnt lgkmcnt(1)
	v_pk_fma_f32 v[14:15], v[34:35], v[42:43], v[14:15]
	v_pk_fma_f32 v[12:13], v[32:33], v[66:67], v[12:13]
	global_store_dwordx4 v[58:59], v[12:15], off offset:-2048 nt
	global_load_dwordx2 v[32:33], v[40:41], off offset:1536
	v_pk_add_f32 v[68:69], v[68:69], v[70:71]
	v_pk_mul_f32 v[70:71], v[14:15], v[14:15]
	v_pk_mul_f32 v[72:73], v[12:13], v[12:13]
	v_pk_add_f32 v[68:69], v[68:69], v[68:69] op_sel:[0,1] op_sel_hi:[1,0]
	v_pk_mov_b32 v[74:75], v[72:73], v[70:71] op_sel:[1,0]
	v_mov_b32_e32 v73, v71
	v_pk_add_f32 v[70:71], v[74:75], v[72:73]
	s_waitcnt vmcnt(0)
	v_lshlrev_b32_e32 v34, 16, v32
	v_and_b32_e32 v35, 0xffff0000, v32
	v_lshlrev_b32_e32 v32, 16, v33
	v_and_b32_e32 v33, 0xffff0000, v33
	v_pk_mul_f32 v[34:35], v[64:65], v[34:35] op_sel_hi:[0,1]
	v_pk_mul_f32 v[32:33], v[64:65], v[32:33] op_sel_hi:[0,1]
	s_waitcnt lgkmcnt(0)
	v_pk_fma_f32 v[18:19], v[38:39], v[32:33], v[18:19]
	v_pk_fma_f32 v[16:17], v[36:37], v[34:35], v[16:17]
	global_store_dwordx4 v[58:59], v[16:19], off offset:-1024 nt
	global_load_dwordx2 v[42:43], v[40:41], off offset:2048
	ds_read_b128 v[32:35], v112 offset:20480
	ds_read_b128 v[36:39], v112 offset:21504
	v_mul_f32_e32 v72, v17, v17
	v_mul_f32_e32 v74, v19, v19
	v_pk_add_f32 v[70:71], v[70:71], v[70:71] op_sel:[0,1] op_sel_hi:[1,0]
	v_pk_fma_f32 v[72:73], v[16:17], v[16:17], v[72:73] op_sel_hi:[1,1,0]
	v_pk_fma_f32 v[74:75], v[18:19], v[18:19], v[74:75] op_sel_hi:[1,1,0]
	s_waitcnt vmcnt(0)
; #define LAS __attribute__((address_space(3)))
; __device__ __forceinline__ unsigned cvt_pk_bf16(float lo, float hi) { unsigned r; asm volatile("v_cvt_pk_bf16_f32 %0, %1, %2" : "=v"(r) : "v"(lo), "v"(hi)); return r; }
; template <bool POST, bool PRE>
; __device__ __forceinline__ void row_core(const Params& P, const RowCfg& c, LAS float* vA, LAS float* vB, LAS float* vP, const bf16_t* RAW, const float* SSQ, bf16_t* H, int row, int lane, f32x4 (&v)[8]) {
;     ...
;         for (int j = 0; j < 8; ++j) { const u32x2 rb = rs[64 * j]; const f32x4 r = (f32x4){__uint_as_float(rb.x << 16), __uint_as_float(rb.x & 0xffff0000u), __uint_as_float(rb.y << 16), __uint_as_float(rb.y & 0xffff0000u)};
;             const f32x4 pv = *(const LAS f32x4*)(vP + j * 256 + lane * 4); v[j] += r * rstd * pv; os[64 * j] = v[j]; }
;     }
;     if (PRE) {
;         float s2 = 0.f;
; #pragma unroll
;         for (int j = 0; j < 8; ++j) s2 += (v[j][0] * v[j][0] + v[j][1] * v[j][1]) + (v[j][2] * v[j][2] + v[j][3] * v[j][3]);
;         s2 = wave_sum(s2);
;         const float rstd2 = rsqrtf(s2 * (1.0f / DM) + EPS);
;         u32x2* hs = (u32x2*)(H + (size_t)row * DM) + lane;
; #pragma unroll
;         for (int j = 0; j < 8; ++j) { const f32x4 a = *(const LAS f32x4*)(vA + j * 256 + lane * 4), b = *(const LAS f32x4*)(vB + j * 256 + lane * 4);
;             v[j] = v[j] * rstd2 * a + b; u32x2 w; w.x = cvt_pk_bf16(v[j][0], v[j][1]); w.y = cvt_pk_bf16(v[j][2], v[j][3]); hs[64 * j] = w; }
	v_lshlrev_b32_e32 v66, 16, v42
	v_and_b32_e32 v67, 0xffff0000, v42
	v_lshlrev_b32_e32 v42, 16, v43
	v_and_b32_e32 v43, 0xffff0000, v43
	v_pk_mul_f32 v[66:67], v[64:65], v[66:67] op_sel_hi:[0,1]
	v_pk_mul_f32 v[42:43], v[64:65], v[42:43] op_sel_hi:[0,1]
	s_waitcnt lgkmcnt(1)
	v_pk_fma_f32 v[22:23], v[34:35], v[42:43], v[22:23]
	v_pk_fma_f32 v[20:21], v[32:33], v[66:67], v[20:21]
	global_store_dwordx4 v[58:59], v[20:23], off nt
	global_load_dwordx2 v[32:33], v[40:41], off offset:2560
	v_mul_f32_e32 v69, v20, v20
	v_mul_f32_e32 v71, v21, v21
	v_mul_f32_e32 v73, v22, v22
	v_mul_f32_e32 v75, v23, v23
	v_pk_add_f32 v[68:69], v[68:69], v[70:71]
	v_pk_add_f32 v[70:71], v[72:73], v[74:75]
	s_waitcnt vmcnt(0)
	v_lshlrev_b32_e32 v34, 16, v32
	v_and_b32_e32 v35, 0xffff0000, v32
	v_lshlrev_b32_e32 v32, 16, v33
	v_and_b32_e32 v33, 0xffff0000, v33
	v_pk_mul_f32 v[34:35], v[64:65], v[34:35] op_sel_hi:[0,1]
	v_pk_mul_f32 v[32:33], v[64:65], v[32:33] op_sel_hi:[0,1]
	s_waitcnt lgkmcnt(0)
	v_pk_fma_f32 v[26:27], v[38:39], v[32:33], v[26:27]
	v_pk_fma_f32 v[24:25], v[36:37], v[34:35], v[24:25]
	global_store_dwordx4 v[58:59], v[24:27], off offset:1024 nt
	global_load_dwordx2 v[42:43], v[40:41], off offset:3072
	ds_read_b128 v[36:39], v112 offset:22528
	ds_read_b128 v[32:35], v112 offset:23552
	v_pk_add_f32 v[68:69], v[68:69], v[70:71]
	v_pk_mul_f32 v[70:71], v[26:27], v[26:27]
	v_pk_mul_f32 v[72:73], v[24:25], v[24:25]
	v_pk_add_f32 v[68:69], v[68:69], v[68:69] op_sel:[0,1] op_sel_hi:[1,0]
	v_pk_mov_b32 v[74:75], v[72:73], v[70:71] op_sel:[1,0]
	v_mov_b32_e32 v73, v71
	v_pk_add_f32 v[70:71], v[74:75], v[72:73]
	s_waitcnt vmcnt(0)
	v_lshlrev_b32_e32 v66, 16, v42
	v_and_b32_e32 v67, 0xffff0000, v42
	v_lshlrev_b32_e32 v42, 16, v43
	v_and_b32_e32 v43, 0xffff0000, v43
	v_pk_mul_f32 v[66:67], v[64:65], v[66:67] op_sel_hi:[0,1]
	v_pk_mul_f32 v[42:43], v[64:65], v[42:43] op_sel_hi:[0,1]
	s_waitcnt lgkmcnt(1)
	v_pk_fma_f32 v[30:31], v[38:39], v[42:43], v[30:31]
	v_pk_fma_f32 v[28:29], v[36:37], v[66:67], v[28:29]
	global_store_dwordx4 v[58:59], v[28:31], off offset:2048 nt
	global_load_dwordx2 v[66:67], v[40:41], off offset:3584
	v_mul_f32_e32 v72, v29, v29
	v_mul_f32_e32 v74, v31, v31
	v_pk_add_f32 v[70:71], v[70:71], v[70:71] op_sel:[0,1] op_sel_hi:[1,0]
	v_pk_fma_f32 v[72:73], v[28:29], v[28:29], v[72:73] op_sel_hi:[1,1,0]
	v_pk_fma_f32 v[74:75], v[30:31], v[30:31], v[74:75] op_sel_hi:[1,1,0]
	ds_read_b128 v[36:39], v112
	ds_read_b128 v[40:43], v112 offset:8192
	s_waitcnt vmcnt(0)
	v_lshlrev_b32_e32 v76, 16, v66
	v_and_b32_e32 v77, 0xffff0000, v66
	v_lshlrev_b32_e32 v66, 16, v67
	v_and_b32_e32 v67, 0xffff0000, v67
	v_pk_mul_f32 v[76:77], v[64:65], v[76:77] op_sel_hi:[0,1]
	v_pk_mul_f32 v[64:65], v[64:65], v[66:67] op_sel_hi:[0,1]
	s_waitcnt lgkmcnt(2)
	v_pk_fma_f32 v[182:183], v[34:35], v[64:65], v[2:3]
	v_pk_fma_f32 v[180:181], v[32:33], v[76:77], v[0:1]
	v_mul_f32_e32 v73, v182, v182
	v_mul_f32_e32 v69, v180, v180
	v_mul_f32_e32 v71, v181, v181
	v_mul_f32_e32 v75, v183, v183
	v_pk_add_f32 v[0:1], v[68:69], v[70:71]
	v_pk_add_f32 v[2:3], v[72:73], v[74:75]
	global_store_dwordx4 v[58:59], v[180:183], off offset:3072 nt
	v_pk_add_f32 v[0:1], v[0:1], v[2:3]
	v_mov_b32_e32 v3, 0
	v_add_f32_e32 v32, v0, v1
	ds_bpermute_b32 v33, v106, v32
	v_mov_b32_e32 v2, 0
	v_mov_b32_e32 v1, 0
	v_mov_b32_e32 v0, 0
	s_waitcnt lgkmcnt(0)
	v_add_f32_e32 v32, v32, v33
	ds_bpermute_b32 v33, v107, v32
	s_waitcnt lgkmcnt(0)
	v_add_f32_e32 v32, v32, v33
	ds_bpermute_b32 v33, v108, v32
	s_waitcnt lgkmcnt(0)
	v_add_f32_e32 v32, v32, v33
	ds_bpermute_b32 v33, v109, v32
	s_waitcnt lgkmcnt(0)
	v_add_f32_e32 v32, v32, v33
	ds_bpermute_b32 v33, v110, v32
	s_waitcnt lgkmcnt(0)
	v_add_f32_e32 v32, v32, v33
	ds_bpermute_b32 v33, v111, v32
	s_waitcnt lgkmcnt(0)
	v_add_f32_e32 v32, v32, v33
	v_fmamk_f32 v32, v32, 0x3a000000, v178
	v_mul_f32_e32 v33, 0x4b800000, v32
	v_cmp_gt_f32_e32 vcc, s17, v32
	s_nop 1
	v_cndmask_b32_e32 v32, v32, v33, vcc
	v_rsq_f32_e32 v32, v32
	s_nop 0
	v_mul_f32_e32 v33, 0x45800000, v32
	v_cndmask_b32_e32 v184, v32, v33, vcc
	v_pk_mul_f32 v[4:5], v[4:5], v[184:185] op_sel_hi:[1,0]
	v_pk_mul_f32 v[6:7], v[6:7], v[184:185] op_sel_hi:[1,0]
	v_pk_fma_f32 v[80:81], v[36:37], v[4:5], v[40:41]
	v_pk_fma_f32 v[76:77], v[38:39], v[6:7], v[42:43]
	v_cvt_pk_bf16_f32 v36, v80, v81
	v_add_co_u32_e32 v186, vcc, s44, v62
	v_cvt_pk_bf16_f32 v37, v76, v77
	ds_read_b128 v[4:7], v112 offset:1024
	ds_read_b128 v[32:35], v112 offset:9216
	v_addc_co_u32_e32 v187, vcc, 0, v63, vcc
	v_pk_mul_f32 v[8:9], v[8:9], v[184:185] op_sel_hi:[1,0]
	v_pk_mul_f32 v[10:11], v[10:11], v[184:185] op_sel_hi:[1,0]
	global_store_dwordx2 v[186:187], v[36:37], off
	s_waitcnt lgkmcnt(0)
	v_pk_fma_f32 v[74:75], v[6:7], v[10:11], v[34:35]
	v_pk_fma_f32 v[78:79], v[4:5], v[8:9], v[32:33]
	v_pk_mul_f32 v[12:13], v[12:13], v[184:185] op_sel_hi:[1,0]
	v_cvt_pk_bf16_f32 v10, v78, v79
	v_cvt_pk_bf16_f32 v11, v74, v75
	ds_read_b128 v[4:7], v112 offset:2048
	ds_read_b128 v[32:35], v112 offset:10240
	v_pk_mul_f32 v[14:15], v[14:15], v[184:185] op_sel_hi:[1,0]
	global_store_dwordx2 v[186:187], v[10:11], off offset:512
	v_pk_mul_f32 v[16:17], v[16:17], v[184:185] op_sel_hi:[1,0]
	v_pk_mul_f32 v[18:19], v[18:19], v[184:185] op_sel_hi:[1,0]
	s_waitcnt lgkmcnt(0)
	v_pk_fma_f32 v[68:69], v[6:7], v[14:15], v[34:35]
	v_pk_fma_f32 v[72:73], v[4:5], v[12:13], v[32:33]
	v_mov_b32_e32 v9, 0
	v_cvt_pk_bf16_f32 v14, v72, v73
	v_cvt_pk_bf16_f32 v15, v68, v69
	ds_read_b128 v[4:7], v112 offset:3072
	ds_read_b128 v[10:13], v112 offset:11264
	global_store_dwordx2 v[186:187], v[14:15], off offset:1024
	v_mov_b32_e32 v8, 0
	s_waitcnt lgkmcnt(0)
; #define LAS __attribute__((address_space(3)))
; __device__ __forceinline__ unsigned cvt_pk_bf16(float lo, float hi) { unsigned r; asm volatile("v_cvt_pk_bf16_f32 %0, %1, %2" : "=v"(r) : "v"(lo), "v"(hi)); return r; }
; template <bool POST, bool PRE>
; __device__ __forceinline__ void row_core(const Params& P, const RowCfg& c, LAS float* vA, LAS float* vB, LAS float* vP, const bf16_t* RAW, const float* SSQ, bf16_t* H, int row, int lane, f32x4 (&v)[8]) {
;     const f32x4* xs = (const f32x4*)(c.xsrc + (size_t)row * DM) + lane;
; #pragma unroll
;     for (int j = 0; j < 8; ++j) v[j] = xs[64 * j];
;     if (POST) {
;         const u32x2* rs = (const u32x2*)(RAW + (size_t)row * DM) + lane;
;         float s = (lane < 32) ? SSQ[(size_t)row * 32 + lane] : 0.f; s = wave_sum(s);
;         const float rstd = rsqrtf(s * (1.0f / DM) + EPS);
;         f32x4* os = (f32x4*)(P.out + (size_t)row * DM) + lane;
; #pragma unroll
;         for (int j = 0; j < 8; ++j) { const u32x2 rb = rs[64 * j]; const f32x4 r = (f32x4){__uint_as_float(rb.x << 16), __uint_as_float(rb.x & 0xffff0000u), __uint_as_float(rb.y << 16), __uint_as_float(rb.y & 0xffff0000u)};
;             const f32x4 pv = *(const LAS f32x4*)(vP + j * 256 + lane * 4); v[j] += r * rstd * pv; os[64 * j] = v[j]; }
;     ...
;         for (int j = 0; j < 8; ++j) { const f32x4 a = *(const LAS f32x4*)(vA + j * 256 + lane * 4), b = *(const LAS f32x4*)(vB + j * 256 + lane * 4);
;             v[j] = v[j] * rstd2 * a + b; u32x2 w; w.x = cvt_pk_bf16(v[j][0], v[j][1]); w.y = cvt_pk_bf16(v[j][2], v[j][3]); hs[64 * j] = w; }
; template <bool POST, bool PRE, bool THIN>
; __device__ __forceinline__ void row_phase(const Ctx& F, const RowCfg c) {
;     ...
;             row_core<POST, PRE>(P, c, vA, vB, vP, RAW, SSQ, H, row, lane, v0);
;             if (hasB) row_core<POST, PRE>(P, c, vA, vB, vP, RAW, SSQ, H, rowB, lane, v1);
	v_pk_fma_f32 v[66:67], v[6:7], v[18:19], v[12:13]
	v_pk_fma_f32 v[70:71], v[4:5], v[16:17], v[10:11]
	v_pk_mul_f32 v[18:19], v[20:21], v[184:185] op_sel_hi:[1,0]
	v_cvt_pk_bf16_f32 v16, v70, v71
	v_cvt_pk_bf16_f32 v17, v66, v67
	ds_read_b128 v[4:7], v112 offset:4096
	ds_read_b128 v[12:15], v112 offset:12288
	v_pk_mul_f32 v[20:21], v[22:23], v[184:185] op_sel_hi:[1,0]
	global_store_dwordx2 v[186:187], v[16:17], off offset:1536
	v_mov_b32_e32 v11, 0
	v_mov_b32_e32 v10, 0
	s_waitcnt lgkmcnt(0)
	v_pk_fma_f32 v[42:43], v[6:7], v[20:21], v[14:15]
	v_pk_fma_f32 v[64:65], v[4:5], v[18:19], v[12:13]
	v_pk_mul_f32 v[18:19], v[24:25], v[184:185] op_sel_hi:[1,0]
	v_cvt_pk_bf16_f32 v16, v64, v65
	v_cvt_pk_bf16_f32 v17, v42, v43
	ds_read_b128 v[4:7], v112 offset:5120
	ds_read_b128 v[12:15], v112 offset:13312
	v_pk_mul_f32 v[20:21], v[26:27], v[184:185] op_sel_hi:[1,0]
	global_store_dwordx2 v[186:187], v[16:17], off offset:2048
	s_waitcnt lgkmcnt(0)
	v_pk_fma_f32 v[40:41], v[20:21], v[6:7], v[14:15]
	v_pk_fma_f32 v[62:63], v[18:19], v[4:5], v[12:13]
	v_pk_mul_f32 v[18:19], v[28:29], v[184:185] op_sel_hi:[1,0]
	v_cvt_pk_bf16_f32 v16, v62, v63
	v_cvt_pk_bf16_f32 v17, v40, v41
	ds_read_b128 v[4:7], v112 offset:6144
	ds_read_b128 v[12:15], v112 offset:14336
	v_pk_mul_f32 v[20:21], v[30:31], v[184:185] op_sel_hi:[1,0]
	global_store_dwordx2 v[186:187], v[16:17], off offset:2560
	s_waitcnt lgkmcnt(0)
	v_pk_fma_f32 v[34:35], v[20:21], v[6:7], v[14:15]
	v_pk_fma_f32 v[38:39], v[18:19], v[4:5], v[12:13]
	v_pk_mul_f32 v[18:19], v[180:181], v[184:185] op_sel_hi:[1,0]
	v_cvt_pk_bf16_f32 v16, v38, v39
	v_cvt_pk_bf16_f32 v17, v34, v35
	ds_read_b128 v[4:7], v112 offset:7168
	ds_read_b128 v[12:15], v112 offset:15360
	v_pk_mul_f32 v[20:21], v[182:183], v[184:185] op_sel_hi:[1,0]
	global_store_dwordx2 v[186:187], v[16:17], off offset:3072
	s_waitcnt lgkmcnt(0)
	v_pk_fma_f32 v[32:33], v[20:21], v[6:7], v[14:15]
	v_pk_fma_f32 v[36:37], v[18:19], v[4:5], v[12:13]
	s_nop 0
	v_cvt_pk_bf16_f32 v4, v36, v37
	v_cvt_pk_bf16_f32 v5, v32, v33
	global_store_dwordx2 v[186:187], v[4:5], off offset:3584
	s_cbranch_scc1 .LBB0_1509
	s_ashr_i32 s39, s38, 31
	s_lshl_b64 s[42:43], s[38:39], 13
	v_lshl_add_u64 v[82:83], v[44:45], 0, s[42:43]
	v_add_co_u32_e32 v0, vcc, 0x1000, v82
	global_load_dwordx4 v[8:11], v[82:83], off nt
	global_load_dwordx4 v[4:7], v[82:83], off offset:1024 nt
	global_load_dwordx4 v[16:19], v[82:83], off offset:2048 nt
	global_load_dwordx4 v[12:15], v[82:83], off offset:3072 nt
	v_addc_co_u32_e32 v1, vcc, 0, v83, vcc
	global_load_dwordx4 v[24:27], v[0:1], off nt
	global_load_dwordx4 v[20:23], v[0:1], off offset:1024 nt
	global_load_dwordx4 v[28:31], v[0:1], off offset:2048 nt
	s_nop 0
	global_load_dwordx4 v[0:3], v[0:1], off offset:3072 nt
	v_mov_b32_e32 v84, 0
	s_and_saveexec_b64 s[42:43], s[0:1]
	s_cbranch_execz .LBB0_1508
	s_lshl_b64 s[46:47], s[38:39], 7
	v_lshl_add_u64 v[84:85], v[46:47], 0, s[46:47]
	global_load_dword v84, v[84:85], off
.LBB0_1508:
	s_or_b64 exec, exec, s[42:43]
	s_lshl_b64 s[42:43], s[38:39], 11
	s_lshl_b64 s[42:43], s[42:43], 1
	v_lshl_add_u64 v[86:87], v[48:49], 0, s[42:43]
	global_load_dwordx2 v[96:97], v[86:87], off
	s_waitcnt vmcnt(1)
	ds_bpermute_b32 v85, v106, v84
	ds_read_b128 v[88:91], v112 offset:16384
	ds_read_b128 v[92:95], v112 offset:17408
	v_lshl_add_u64 v[186:187], v[50:51], 0, s[42:43]
	s_waitcnt lgkmcnt(2)
	v_add_f32_e32 v84, v84, v85
	ds_bpermute_b32 v85, v107, v84
	s_waitcnt lgkmcnt(0)
	v_add_f32_e32 v84, v84, v85
	ds_bpermute_b32 v85, v108, v84
	s_waitcnt lgkmcnt(0)
	v_add_f32_e32 v84, v84, v85
	ds_bpermute_b32 v85, v109, v84
	s_waitcnt lgkmcnt(0)
	v_add_f32_e32 v84, v84, v85
	ds_bpermute_b32 v85, v110, v84
	s_waitcnt lgkmcnt(0)
	v_add_f32_e32 v84, v84, v85
	ds_bpermute_b32 v85, v111, v84
	s_waitcnt lgkmcnt(0)
	v_add_f32_e32 v84, v84, v85
	v_fmamk_f32 v84, v84, 0x3a000000, v178
	v_mul_f32_e32 v85, 0x4b800000, v84
	v_cmp_gt_f32_e32 vcc, s17, v84
	s_waitcnt vmcnt(0)
	v_lshlrev_b32_e32 v98, 16, v96
	v_cndmask_b32_e32 v84, v84, v85, vcc
	v_rsq_f32_e32 v84, v84
	v_and_b32_e32 v99, 0xffff0000, v96
	v_lshlrev_b32_e32 v96, 16, v97
	v_and_b32_e32 v97, 0xffff0000, v97
	v_mul_f32_e32 v85, 0x45800000, v84
	v_cndmask_b32_e32 v84, v84, v85, vcc
	v_pk_mul_f32 v[98:99], v[84:85], v[98:99] op_sel_hi:[0,1]
	v_pk_mul_f32 v[96:97], v[84:85], v[96:97] op_sel_hi:[0,1]
	v_pk_fma_f32 v[10:11], v[90:91], v[96:97], v[10:11]
	v_pk_fma_f32 v[8:9], v[88:89], v[98:99], v[8:9]
	global_store_dwordx4 v[82:83], v[8:11], off nt
	global_load_dwordx2 v[88:89], v[86:87], off offset:512
	s_waitcnt vmcnt(0)
	v_lshlrev_b32_e32 v90, 16, v88
	v_and_b32_e32 v91, 0xffff0000, v88
	v_lshlrev_b32_e32 v88, 16, v89
	v_and_b32_e32 v89, 0xffff0000, v89
	v_pk_mul_f32 v[90:91], v[84:85], v[90:91] op_sel_hi:[0,1]
	v_pk_mul_f32 v[88:89], v[84:85], v[88:89] op_sel_hi:[0,1]
	v_pk_fma_f32 v[6:7], v[94:95], v[88:89], v[6:7]
	v_pk_fma_f32 v[4:5], v[92:93], v[90:91], v[4:5]
	global_store_dwordx4 v[82:83], v[4:7], off offset:1024 nt
	global_load_dwordx2 v[96:97], v[86:87], off offset:1024
	ds_read_b128 v[88:91], v112 offset:18432
	ds_read_b128 v[92:95], v112 offset:19456
	s_waitcnt vmcnt(0)
	v_lshlrev_b32_e32 v98, 16, v96
	v_and_b32_e32 v99, 0xffff0000, v96
	v_lshlrev_b32_e32 v96, 16, v97
	v_and_b32_e32 v97, 0xffff0000, v97
	v_pk_mul_f32 v[98:99], v[84:85], v[98:99] op_sel_hi:[0,1]
	v_pk_mul_f32 v[96:97], v[84:85], v[96:97] op_sel_hi:[0,1]
	s_waitcnt lgkmcnt(1)
	v_pk_fma_f32 v[18:19], v[90:91], v[96:97], v[18:19]
	v_pk_fma_f32 v[16:17], v[88:89], v[98:99], v[16:17]
	global_store_dwordx4 v[82:83], v[16:19], off offset:2048 nt
	global_load_dwordx2 v[88:89], v[86:87], off offset:1536
	v_lshl_add_u64 v[98:99], v[82:83], 0, s[24:25]
	s_waitcnt vmcnt(0)
; #define LAS __attribute__((address_space(3)))
; template <bool POST, bool PRE>
; __device__ __forceinline__ void row_core(const Params& P, const RowCfg& c, LAS float* vA, LAS float* vB, LAS float* vP, const bf16_t* RAW, const float* SSQ, bf16_t* H, int row, int lane, f32x4 (&v)[8]) {
;     ...
;         f32x4* os = (f32x4*)(P.out + (size_t)row * DM) + lane;
; #pragma unroll
;         for (int j = 0; j < 8; ++j) { const u32x2 rb = rs[64 * j]; const f32x4 r = (f32x4){__uint_as_float(rb.x << 16), __uint_as_float(rb.x & 0xffff0000u), __uint_as_float(rb.y << 16), __uint_as_float(rb.y & 0xffff0000u)};
;             const f32x4 pv = *(const LAS f32x4*)(vP + j * 256 + lane * 4); v[j] += r * rstd * pv; os[64 * j] = v[j]; }
;     ...
;         for (int j = 0; j < 8; ++j) s2 += (v[j][0] * v[j][0] + v[j][1] * v[j][1]) + (v[j][2] * v[j][2] + v[j][3] * v[j][3]);
	v_lshlrev_b32_e32 v90, 16, v88
	v_and_b32_e32 v91, 0xffff0000, v88
	v_lshlrev_b32_e32 v88, 16, v89
	v_and_b32_e32 v89, 0xffff0000, v89
	v_pk_mul_f32 v[90:91], v[84:85], v[90:91] op_sel_hi:[0,1]
	v_pk_mul_f32 v[88:89], v[84:85], v[88:89] op_sel_hi:[0,1]
	s_waitcnt lgkmcnt(0)
	v_pk_fma_f32 v[14:15], v[94:95], v[88:89], v[14:15]
	v_pk_fma_f32 v[12:13], v[92:93], v[90:91], v[12:13]
	global_store_dwordx4 v[82:83], v[12:15], off offset:3072 nt
	global_load_dwordx2 v[96:97], v[86:87], off offset:2048
	ds_read_b128 v[88:91], v112 offset:20480
	ds_read_b128 v[92:95], v112 offset:21504
	s_waitcnt vmcnt(0)
	v_lshlrev_b32_e32 v100, 16, v96
	v_and_b32_e32 v101, 0xffff0000, v96
	v_lshlrev_b32_e32 v96, 16, v97
	v_and_b32_e32 v97, 0xffff0000, v97
	v_pk_mul_f32 v[100:101], v[84:85], v[100:101] op_sel_hi:[0,1]
	v_pk_mul_f32 v[96:97], v[84:85], v[96:97] op_sel_hi:[0,1]
	s_waitcnt lgkmcnt(1)
	v_pk_fma_f32 v[26:27], v[90:91], v[96:97], v[26:27]
	v_pk_fma_f32 v[24:25], v[88:89], v[100:101], v[24:25]
	global_store_dwordx4 v[98:99], v[24:27], off nt
	global_load_dwordx2 v[88:89], v[86:87], off offset:2560
	v_lshl_add_u64 v[90:91], v[82:83], 0, s[30:31]
	v_lshl_add_u64 v[98:99], v[82:83], 0, s[34:35]
	s_waitcnt vmcnt(0)
	v_lshlrev_b32_e32 v96, 16, v88
	v_and_b32_e32 v97, 0xffff0000, v88
	v_lshlrev_b32_e32 v88, 16, v89
	v_and_b32_e32 v89, 0xffff0000, v89
	v_pk_mul_f32 v[96:97], v[84:85], v[96:97] op_sel_hi:[0,1]
	v_pk_mul_f32 v[88:89], v[84:85], v[88:89] op_sel_hi:[0,1]
	s_waitcnt lgkmcnt(0)
	v_pk_fma_f32 v[22:23], v[94:95], v[88:89], v[22:23]
	v_pk_fma_f32 v[20:21], v[92:93], v[96:97], v[20:21]
	global_store_dwordx4 v[90:91], v[20:23], off nt
	global_load_dwordx2 v[96:97], v[86:87], off offset:3072
	ds_read_b128 v[88:91], v112 offset:22528
	ds_read_b128 v[92:95], v112 offset:23552
	s_waitcnt vmcnt(0)
	v_lshlrev_b32_e32 v100, 16, v96
	v_and_b32_e32 v101, 0xffff0000, v96
	v_lshlrev_b32_e32 v96, 16, v97
	v_and_b32_e32 v97, 0xffff0000, v97
	v_pk_mul_f32 v[100:101], v[84:85], v[100:101] op_sel_hi:[0,1]
	v_pk_mul_f32 v[96:97], v[84:85], v[96:97] op_sel_hi:[0,1]
	s_waitcnt lgkmcnt(1)
	v_pk_fma_f32 v[30:31], v[90:91], v[96:97], v[30:31]
	v_pk_fma_f32 v[28:29], v[88:89], v[100:101], v[28:29]
	global_store_dwordx4 v[98:99], v[28:31], off nt
	global_load_dwordx2 v[86:87], v[86:87], off offset:3584
	v_mov_b32_e32 v90, v9
	v_mov_b32_e32 v98, v11
	v_mov_b32_e32 v91, v5
	v_mov_b32_e32 v99, v7
	v_mov_b32_e32 v88, v8
	v_mov_b32_e32 v96, v10
	v_mov_b32_e32 v89, v4
	v_mov_b32_e32 v97, v6
	v_pk_mul_f32 v[90:91], v[90:91], v[90:91]
	v_pk_mul_f32 v[98:99], v[98:99], v[98:99]
	v_pk_fma_f32 v[88:89], v[88:89], v[88:89], v[90:91]
	v_pk_fma_f32 v[90:91], v[96:97], v[96:97], v[98:99]
	v_pk_mul_f32 v[96:97], v[16:17], v[16:17]
	v_pk_add_f32 v[88:89], v[88:89], v[90:91]
	v_pk_mul_f32 v[90:91], v[18:19], v[18:19]
	v_pk_add_f32 v[88:89], v[88:89], v[88:89] op_sel:[0,1] op_sel_hi:[1,0]
	v_pk_mov_b32 v[98:99], v[96:97], v[90:91] op_sel:[1,0]
	v_mov_b32_e32 v97, v91
	v_pk_add_f32 v[90:91], v[98:99], v[96:97]
	v_mul_f32_e32 v96, v13, v13
	v_mul_f32_e32 v98, v15, v15
	v_pk_add_f32 v[90:91], v[90:91], v[90:91] op_sel:[0,1] op_sel_hi:[1,0]
	v_pk_fma_f32 v[96:97], v[12:13], v[12:13], v[96:97] op_sel_hi:[1,1,0]
	v_pk_fma_f32 v[98:99], v[14:15], v[14:15], v[98:99] op_sel_hi:[1,1,0]
	v_mul_f32_e32 v89, v24, v24
	v_mul_f32_e32 v91, v25, v25
	v_mul_f32_e32 v97, v26, v26
	v_mul_f32_e32 v99, v27, v27
	v_pk_add_f32 v[88:89], v[88:89], v[90:91]
	v_pk_add_f32 v[90:91], v[96:97], v[98:99]
	v_pk_mul_f32 v[96:97], v[20:21], v[20:21]
	v_pk_add_f32 v[88:89], v[88:89], v[90:91]
	v_pk_mul_f32 v[90:91], v[22:23], v[22:23]
	v_pk_add_f32 v[88:89], v[88:89], v[88:89] op_sel:[0,1] op_sel_hi:[1,0]
	v_pk_mov_b32 v[98:99], v[96:97], v[90:91] op_sel:[1,0]
	v_mov_b32_e32 v97, v91
	v_pk_add_f32 v[90:91], v[98:99], v[96:97]
	v_mul_f32_e32 v96, v29, v29
	v_mul_f32_e32 v98, v31, v31
	v_pk_add_f32 v[90:91], v[90:91], v[90:91] op_sel:[0,1] op_sel_hi:[1,0]
	v_pk_fma_f32 v[96:97], v[28:29], v[28:29], v[96:97] op_sel_hi:[1,1,0]
	v_pk_fma_f32 v[98:99], v[30:31], v[30:31], v[98:99] op_sel_hi:[1,1,0]
	s_waitcnt vmcnt(0)
	v_lshlrev_b32_e32 v100, 16, v86
	v_and_b32_e32 v101, 0xffff0000, v86
	v_lshlrev_b32_e32 v86, 16, v87
	v_and_b32_e32 v87, 0xffff0000, v87
	v_pk_mul_f32 v[100:101], v[84:85], v[100:101] op_sel_hi:[0,1]
	v_pk_mul_f32 v[84:85], v[84:85], v[86:87] op_sel_hi:[0,1]
	s_waitcnt lgkmcnt(0)
; #define LAS __attribute__((address_space(3)))
; __device__ __forceinline__ unsigned cvt_pk_bf16(float lo, float hi) { unsigned r; asm volatile("v_cvt_pk_bf16_f32 %0, %1, %2" : "=v"(r) : "v"(lo), "v"(hi)); return r; }
; template <bool POST, bool PRE>
; __device__ __forceinline__ void row_core(const Params& P, const RowCfg& c, LAS float* vA, LAS float* vB, LAS float* vP, const bf16_t* RAW, const float* SSQ, bf16_t* H, int row, int lane, f32x4 (&v)[8]) {
;     ...
;             const f32x4 pv = *(const LAS f32x4*)(vP + j * 256 + lane * 4); v[j] += r * rstd * pv; os[64 * j] = v[j]; }
;     ...
;         s2 = wave_sum(s2);
;         const float rstd2 = rsqrtf(s2 * (1.0f / DM) + EPS);
;         u32x2* hs = (u32x2*)(H + (size_t)row * DM) + lane;
; #pragma unroll
;         for (int j = 0; j < 8; ++j) { const f32x4 a = *(const LAS f32x4*)(vA + j * 256 + lane * 4), b = *(const LAS f32x4*)(vB + j * 256 + lane * 4);
;             v[j] = v[j] * rstd2 * a + b; u32x2 w; w.x = cvt_pk_bf16(v[j][0], v[j][1]); w.y = cvt_pk_bf16(v[j][2], v[j][3]); hs[64 * j] = w; }
	v_pk_fma_f32 v[182:183], v[94:95], v[84:85], v[2:3]
	v_pk_fma_f32 v[180:181], v[92:93], v[100:101], v[0:1]
	v_mul_f32_e32 v97, v182, v182
	v_mul_f32_e32 v89, v180, v180
	v_mul_f32_e32 v91, v181, v181
	v_mul_f32_e32 v99, v183, v183
	v_pk_add_f32 v[0:1], v[88:89], v[90:91]
	v_pk_add_f32 v[2:3], v[96:97], v[98:99]
	v_lshl_add_u64 v[86:87], v[82:83], 0, s[36:37]
	v_pk_add_f32 v[0:1], v[0:1], v[2:3]
	s_nop 0
	v_add_f32_e32 v0, v0, v1
	ds_bpermute_b32 v1, v106, v0
	s_waitcnt lgkmcnt(0)
	v_add_f32_e32 v0, v0, v1
	ds_bpermute_b32 v1, v107, v0
	s_waitcnt lgkmcnt(0)
	v_add_f32_e32 v0, v0, v1
	ds_bpermute_b32 v1, v108, v0
	s_waitcnt lgkmcnt(0)
	v_add_f32_e32 v0, v0, v1
	ds_bpermute_b32 v1, v109, v0
	s_waitcnt lgkmcnt(0)
	v_add_f32_e32 v0, v0, v1
	ds_bpermute_b32 v1, v110, v0
	s_waitcnt lgkmcnt(0)
	v_add_f32_e32 v0, v0, v1
	ds_bpermute_b32 v1, v111, v0
	s_waitcnt lgkmcnt(0)
	v_add_f32_e32 v0, v0, v1
	v_fmamk_f32 v0, v0, 0x3a000000, v178
	v_mul_f32_e32 v1, 0x4b800000, v0
	v_cmp_gt_f32_e32 vcc, s17, v0
	s_nop 1
	v_cndmask_b32_e32 v0, v0, v1, vcc
	v_rsq_f32_e32 v88, v0
	ds_read_b128 v[0:3], v112
	ds_read_b128 v[82:85], v112 offset:8192
	global_store_dwordx4 v[86:87], v[180:183], off nt
	v_mul_f32_e32 v86, 0x45800000, v88
	v_cndmask_b32_e32 v184, v88, v86, vcc
	v_pk_mul_f32 v[86:87], v[8:9], v[184:185] op_sel_hi:[1,0]
	v_pk_mul_f32 v[8:9], v[10:11], v[184:185] op_sel_hi:[1,0]
	s_waitcnt lgkmcnt(0)
	v_pk_fma_f32 v[10:11], v[0:1], v[86:87], v[82:83]
	v_pk_fma_f32 v[8:9], v[2:3], v[8:9], v[84:85]
	v_cvt_pk_bf16_f32 v86, v10, v11
	v_pk_mul_f32 v[4:5], v[4:5], v[184:185] op_sel_hi:[1,0]
	v_cvt_pk_bf16_f32 v87, v8, v9
	ds_read_b128 v[0:3], v112 offset:1024
	ds_read_b128 v[82:85], v112 offset:9216
	v_pk_mul_f32 v[6:7], v[6:7], v[184:185] op_sel_hi:[1,0]
	global_store_dwordx2 v[186:187], v[86:87], off
	v_pk_mul_f32 v[16:17], v[16:17], v[184:185] op_sel_hi:[1,0]
	v_pk_mul_f32 v[18:19], v[18:19], v[184:185] op_sel_hi:[1,0]
	s_waitcnt lgkmcnt(0)
	v_pk_fma_f32 v[102:103], v[2:3], v[6:7], v[84:85]
	v_pk_fma_f32 v[104:105], v[0:1], v[4:5], v[82:83]
	v_pk_mul_f32 v[12:13], v[12:13], v[184:185] op_sel_hi:[1,0]
	v_cvt_pk_bf16_f32 v82, v104, v105
	v_cvt_pk_bf16_f32 v83, v102, v103
	ds_read_b128 v[0:3], v112 offset:2048
	ds_read_b128 v[4:7], v112 offset:10240
	global_store_dwordx2 v[186:187], v[82:83], off offset:512
	v_pk_mul_f32 v[14:15], v[14:15], v[184:185] op_sel_hi:[1,0]
	s_waitcnt lgkmcnt(0)
	v_pk_fma_f32 v[96:97], v[2:3], v[18:19], v[6:7]
	v_pk_fma_f32 v[100:101], v[0:1], v[16:17], v[4:5]
	v_pk_mul_f32 v[18:19], v[182:183], v[184:185] op_sel_hi:[1,0]
	v_cvt_pk_bf16_f32 v16, v100, v101
	v_cvt_pk_bf16_f32 v17, v96, v97
	ds_read_b128 v[0:3], v112 offset:3072
	ds_read_b128 v[4:7], v112 offset:11264
	global_store_dwordx2 v[186:187], v[16:17], off offset:1024
	v_pk_mul_f32 v[16:17], v[26:27], v[184:185] op_sel_hi:[1,0]
	s_waitcnt lgkmcnt(0)
	v_pk_fma_f32 v[94:95], v[2:3], v[14:15], v[6:7]
	v_pk_fma_f32 v[98:99], v[0:1], v[12:13], v[4:5]
	v_pk_mul_f32 v[14:15], v[24:25], v[184:185] op_sel_hi:[1,0]
	v_cvt_pk_bf16_f32 v12, v98, v99
	v_cvt_pk_bf16_f32 v13, v94, v95
	ds_read_b128 v[0:3], v112 offset:4096
	ds_read_b128 v[4:7], v112 offset:12288
	global_store_dwordx2 v[186:187], v[12:13], off offset:1536
	s_waitcnt lgkmcnt(0)
	v_pk_fma_f32 v[88:89], v[2:3], v[16:17], v[6:7]
	v_pk_fma_f32 v[92:93], v[0:1], v[14:15], v[4:5]
	v_pk_mul_f32 v[14:15], v[20:21], v[184:185] op_sel_hi:[1,0]
	v_cvt_pk_bf16_f32 v12, v92, v93
	v_cvt_pk_bf16_f32 v13, v88, v89
	ds_read_b128 v[0:3], v112 offset:5120
	ds_read_b128 v[4:7], v112 offset:13312
	v_pk_mul_f32 v[16:17], v[22:23], v[184:185] op_sel_hi:[1,0]
	global_store_dwordx2 v[186:187], v[12:13], off offset:2048
	s_waitcnt lgkmcnt(0)
	v_pk_fma_f32 v[86:87], v[16:17], v[2:3], v[6:7]
	v_pk_fma_f32 v[90:91], v[14:15], v[0:1], v[4:5]
	v_pk_mul_f32 v[6:7], v[28:29], v[184:185] op_sel_hi:[1,0]
	v_cvt_pk_bf16_f32 v0, v90, v91
	v_cvt_pk_bf16_f32 v1, v86, v87
	ds_read_b128 v[2:5], v112 offset:6144
	ds_read_b128 v[12:15], v112 offset:14336
	v_pk_mul_f32 v[16:17], v[30:31], v[184:185] op_sel_hi:[1,0]
	global_store_dwordx2 v[186:187], v[0:1], off offset:2560
	s_waitcnt lgkmcnt(0)
	v_pk_fma_f32 v[0:1], v[16:17], v[4:5], v[14:15]
	v_pk_fma_f32 v[84:85], v[6:7], v[2:3], v[12:13]
	v_pk_mul_f32 v[16:17], v[180:181], v[184:185] op_sel_hi:[1,0]
	v_cvt_pk_bf16_f32 v6, v84, v85
	v_cvt_pk_bf16_f32 v7, v0, v1
	ds_read_b128 v[2:5], v112 offset:7168
	ds_read_b128 v[12:15], v112 offset:15360
	global_store_dwordx2 v[186:187], v[6:7], off offset:3072
	s_waitcnt lgkmcnt(0)
	v_pk_fma_f32 v[82:83], v[18:19], v[4:5], v[14:15]
	v_pk_fma_f32 v[2:3], v[16:17], v[2:3], v[12:13]
	s_nop 0
	v_cvt_pk_bf16_f32 v4, v2, v3
	v_cvt_pk_bf16_f32 v5, v82, v83
	global_store_dwordx2 v[186:187], v[4:5], off offset:3584

; #define LAS __attribute__((address_space(3)))
; template <bool POST, bool PRE>
; __device__ __forceinline__ void row_core(const Params& P, const RowCfg& c, LAS float* vA, LAS float* vB, LAS float* vP, const bf16_t* RAW, const float* SSQ, bf16_t* H, int row, int lane, f32x4 (&v)[8]) {
;     ...
;         const u32x2* rs = (const u32x2*)(RAW + (size_t)row * DM) + lane;
;         float s = (lane < 32) ? SSQ[(size_t)row * 32 + lane] : 0.f; s = wave_sum(s);
;         const float rstd = rsqrtf(s * (1.0f / DM) + EPS);
;         f32x4* os = (f32x4*)(P.out + (size_t)row * DM) + lane;
; #pragma unroll
;         for (int j = 0; j < 8; ++j) { const u32x2 rb = rs[64 * j]; const f32x4 r = (f32x4){__uint_as_float(rb.x << 16), __uint_as_float(rb.x & 0xffff0000u), __uint_as_float(rb.y << 16), __uint_as_float(rb.y & 0xffff0000u)};
;             const f32x4 pv = *(const LAS f32x4*)(vP + j * 256 + lane * 4); v[j] += r * rstd * pv; os[64 * j] = v[j]; }
.LBB0_2053:
	s_or_b64 exec, exec, s[0:1]
	v_lshl_add_u64 v[40:41], s[92:93], 0, v[38:39]
	v_add_co_u32_e64 v58, s[0:1], s7, v40
	s_waitcnt vmcnt(0)
	ds_bpermute_b32 v49, v43, v42
	v_addc_co_u32_e64 v59, s[0:1], 0, v41, s[0:1]
	global_load_dwordx2 v[60:61], v[58:59], off
	s_add_i32 s6, s6, s8
	s_waitcnt lgkmcnt(0)
	v_add_f32_e32 v42, v42, v49
	ds_bpermute_b32 v49, v44, v42
	v_lshl_add_u64 v[34:35], v[34:35], 0, s[10:11]
	s_cmpk_lt_i32 s6, 0x4000
	v_lshl_add_u64 v[38:39], v[38:39], 0, s[14:15]
	s_waitcnt lgkmcnt(0)
	v_add_f32_e32 v42, v42, v49
	ds_bpermute_b32 v49, v45, v42
	s_waitcnt lgkmcnt(0)
	v_add_f32_e32 v42, v42, v49
	ds_bpermute_b32 v49, v46, v42
	s_waitcnt lgkmcnt(0)
	v_add_f32_e32 v42, v42, v49
	ds_bpermute_b32 v49, v47, v42
	s_waitcnt lgkmcnt(0)
	v_add_f32_e32 v42, v42, v49
	ds_bpermute_b32 v49, v48, v42
	s_waitcnt lgkmcnt(0)
	v_add_f32_e32 v42, v42, v49
	v_fmamk_f32 v42, v42, 0x3a000000, v33
	v_mul_f32_e32 v49, 0x4b800000, v42
	v_cmp_gt_f32_e64 s[0:1], s3, v42
	s_waitcnt vmcnt(0)
	v_and_b32_e32 v63, 0xffff0000, v60
	v_cndmask_b32_e64 v42, v42, v49, s[0:1]
	v_rsq_f32_e32 v42, v42
	v_add_u32_e32 v49, 0, v32
	ds_read_b128 v[50:53], v49 offset:16384
	ds_read_b128 v[54:57], v49 offset:17408
	v_mul_f32_e32 v62, 0x45800000, v42
	v_cndmask_b32_e64 v42, v42, v62, s[0:1]
	v_lshlrev_b32_e32 v62, 16, v60
	v_lshlrev_b32_e32 v60, 16, v61
	v_and_b32_e32 v61, 0xffff0000, v61
	v_pk_mul_f32 v[62:63], v[42:43], v[62:63] op_sel_hi:[0,1]
	v_pk_mul_f32 v[60:61], v[42:43], v[60:61] op_sel_hi:[0,1]
	s_waitcnt lgkmcnt(1)
	v_pk_fma_f32 v[22:23], v[52:53], v[60:61], v[22:23]
	v_pk_fma_f32 v[20:21], v[50:51], v[62:63], v[20:21]
	global_store_dwordx4 v[36:37], v[20:23], off offset:-4096 nt
	global_load_dwordx2 v[50:51], v[58:59], off offset:512
	s_waitcnt vmcnt(0)
	v_lshlrev_b32_e32 v52, 16, v50
	v_and_b32_e32 v53, 0xffff0000, v50
	v_lshlrev_b32_e32 v50, 16, v51
	v_and_b32_e32 v51, 0xffff0000, v51
	v_pk_mul_f32 v[52:53], v[42:43], v[52:53] op_sel_hi:[0,1]
	v_pk_mul_f32 v[50:51], v[42:43], v[50:51] op_sel_hi:[0,1]
	s_waitcnt lgkmcnt(0)
	v_pk_fma_f32 v[14:15], v[56:57], v[50:51], v[14:15]
	v_pk_fma_f32 v[12:13], v[54:55], v[52:53], v[12:13]
	global_store_dwordx4 v[36:37], v[12:15], off offset:-3072 nt
	global_load_dwordx2 v[60:61], v[58:59], off offset:1024
	ds_read_b128 v[50:53], v49 offset:18432
	ds_read_b128 v[54:57], v49 offset:19456
	s_waitcnt vmcnt(0)
	v_lshlrev_b32_e32 v62, 16, v60
	v_and_b32_e32 v63, 0xffff0000, v60
	v_lshlrev_b32_e32 v60, 16, v61
	v_and_b32_e32 v61, 0xffff0000, v61
	v_pk_mul_f32 v[62:63], v[42:43], v[62:63] op_sel_hi:[0,1]
	v_pk_mul_f32 v[60:61], v[42:43], v[60:61] op_sel_hi:[0,1]
	s_waitcnt lgkmcnt(1)
	v_pk_fma_f32 v[30:31], v[52:53], v[60:61], v[30:31]
	v_pk_fma_f32 v[28:29], v[50:51], v[62:63], v[28:29]
	global_store_dwordx4 v[36:37], v[28:31], off offset:-2048 nt
	global_load_dwordx2 v[50:51], v[58:59], off offset:1536
	s_waitcnt vmcnt(0)
	v_lshlrev_b32_e32 v52, 16, v50
	v_and_b32_e32 v53, 0xffff0000, v50
	v_lshlrev_b32_e32 v50, 16, v51
	v_and_b32_e32 v51, 0xffff0000, v51
	v_pk_mul_f32 v[52:53], v[42:43], v[52:53] op_sel_hi:[0,1]
	v_pk_mul_f32 v[50:51], v[42:43], v[50:51] op_sel_hi:[0,1]
	s_waitcnt lgkmcnt(0)
	v_pk_fma_f32 v[26:27], v[56:57], v[50:51], v[26:27]
	v_pk_fma_f32 v[24:25], v[54:55], v[52:53], v[24:25]
	global_store_dwordx4 v[36:37], v[24:27], off offset:-1024 nt
	global_load_dwordx2 v[60:61], v[58:59], off offset:2048
	ds_read_b128 v[50:53], v49 offset:20480
	ds_read_b128 v[54:57], v49 offset:21504
	s_waitcnt vmcnt(0)
	v_lshlrev_b32_e32 v62, 16, v60
	v_and_b32_e32 v63, 0xffff0000, v60
	v_lshlrev_b32_e32 v60, 16, v61
	v_and_b32_e32 v61, 0xffff0000, v61
	v_pk_mul_f32 v[62:63], v[42:43], v[62:63] op_sel_hi:[0,1]
	v_pk_mul_f32 v[60:61], v[42:43], v[60:61] op_sel_hi:[0,1]
	s_waitcnt lgkmcnt(1)
	v_pk_fma_f32 v[6:7], v[52:53], v[60:61], v[6:7]
	v_pk_fma_f32 v[4:5], v[50:51], v[62:63], v[4:5]
	global_store_dwordx4 v[36:37], v[4:7], off nt
	global_load_dwordx2 v[50:51], v[58:59], off offset:2560
	s_waitcnt vmcnt(0)
	v_lshlrev_b32_e32 v52, 16, v50
	v_and_b32_e32 v53, 0xffff0000, v50
	v_lshlrev_b32_e32 v50, 16, v51
	v_and_b32_e32 v51, 0xffff0000, v51
	v_pk_mul_f32 v[52:53], v[42:43], v[52:53] op_sel_hi:[0,1]
	v_pk_mul_f32 v[50:51], v[42:43], v[50:51] op_sel_hi:[0,1]
	s_waitcnt lgkmcnt(0)
	v_pk_fma_f32 v[10:11], v[56:57], v[50:51], v[10:11]
	v_pk_fma_f32 v[8:9], v[54:55], v[52:53], v[8:9]
	global_store_dwordx4 v[36:37], v[8:11], off offset:1024 nt
	global_load_dwordx2 v[60:61], v[58:59], off offset:3072
	ds_read_b128 v[50:53], v49 offset:22528
	ds_read_b128 v[54:57], v49 offset:23552
	s_waitcnt vmcnt(0)
	v_lshlrev_b32_e32 v62, 16, v60
	v_and_b32_e32 v63, 0xffff0000, v60
	v_lshlrev_b32_e32 v60, 16, v61
	v_and_b32_e32 v61, 0xffff0000, v61
	v_pk_mul_f32 v[62:63], v[42:43], v[62:63] op_sel_hi:[0,1]
	v_pk_mul_f32 v[60:61], v[42:43], v[60:61] op_sel_hi:[0,1]
	s_waitcnt lgkmcnt(1)
; #define LAS __attribute__((address_space(3)))
; template <bool POST, bool PRE>
; __device__ __forceinline__ void row_core(const Params& P, const RowCfg& c, LAS float* vA, LAS float* vB, LAS float* vP, const bf16_t* RAW, const float* SSQ, bf16_t* H, int row, int lane, f32x4 (&v)[8]) {
;     ...
;             const f32x4 pv = *(const LAS f32x4*)(vP + j * 256 + lane * 4); v[j] += r * rstd * pv; os[64 * j] = v[j]; }
;     ...
;         float s2 = 0.f;
; #pragma unroll
;         for (int j = 0; j < 8; ++j) s2 += (v[j][0] * v[j][0] + v[j][1] * v[j][1]) + (v[j][2] * v[j][2] + v[j][3] * v[j][3]);
;         s2 = wave_sum(s2);
;         const float rstd2 = rsqrtf(s2 * (1.0f / DM) + EPS);
	v_pk_fma_f32 v[18:19], v[52:53], v[60:61], v[18:19]
	v_pk_fma_f32 v[16:17], v[50:51], v[62:63], v[16:17]
	global_store_dwordx4 v[36:37], v[16:19], off offset:2048 nt
	global_load_dwordx2 v[50:51], v[58:59], off offset:3584
	v_mov_b32_e32 v58, v21
	v_mov_b32_e32 v62, v23
	v_mov_b32_e32 v59, v13
	v_mov_b32_e32 v63, v15
	v_mov_b32_e32 v52, v20
	v_mov_b32_e32 v60, v22
	v_mov_b32_e32 v53, v12
	v_mov_b32_e32 v61, v14
	v_pk_mul_f32 v[58:59], v[58:59], v[58:59]
	v_pk_mul_f32 v[62:63], v[62:63], v[62:63]
	v_pk_fma_f32 v[52:53], v[52:53], v[52:53], v[58:59]
	v_pk_fma_f32 v[58:59], v[60:61], v[60:61], v[62:63]
	v_pk_mul_f32 v[60:61], v[28:29], v[28:29]
	v_pk_add_f32 v[52:53], v[52:53], v[58:59]
	v_pk_mul_f32 v[58:59], v[30:31], v[30:31]
	v_pk_add_f32 v[52:53], v[52:53], v[52:53] op_sel:[0,1] op_sel_hi:[1,0]
	v_pk_mov_b32 v[62:63], v[60:61], v[58:59] op_sel:[1,0]
	v_mov_b32_e32 v61, v59
	v_pk_add_f32 v[58:59], v[62:63], v[60:61]
	v_mul_f32_e32 v60, v25, v25
	v_mul_f32_e32 v62, v27, v27
	v_pk_add_f32 v[58:59], v[58:59], v[58:59] op_sel:[0,1] op_sel_hi:[1,0]
	v_pk_fma_f32 v[60:61], v[24:25], v[24:25], v[60:61] op_sel_hi:[1,1,0]
	v_pk_fma_f32 v[62:63], v[26:27], v[26:27], v[62:63] op_sel_hi:[1,1,0]
	v_mul_f32_e32 v53, v4, v4
	v_mul_f32_e32 v59, v5, v5
	v_mul_f32_e32 v61, v6, v6
	v_mul_f32_e32 v63, v7, v7
	v_pk_add_f32 v[52:53], v[52:53], v[58:59]
	v_pk_add_f32 v[58:59], v[60:61], v[62:63]
	v_pk_mul_f32 v[60:61], v[8:9], v[8:9]
	v_pk_add_f32 v[52:53], v[52:53], v[58:59]
	v_pk_mul_f32 v[58:59], v[10:11], v[10:11]
	v_pk_add_f32 v[52:53], v[52:53], v[52:53] op_sel:[0,1] op_sel_hi:[1,0]
	v_pk_mov_b32 v[62:63], v[60:61], v[58:59] op_sel:[1,0]
	v_mov_b32_e32 v61, v59
	v_pk_add_f32 v[58:59], v[62:63], v[60:61]
	v_mul_f32_e32 v60, v17, v17
	v_mul_f32_e32 v62, v19, v19
	v_pk_add_f32 v[58:59], v[58:59], v[58:59] op_sel:[0,1] op_sel_hi:[1,0]
	v_pk_fma_f32 v[60:61], v[16:17], v[16:17], v[60:61] op_sel_hi:[1,1,0]
	v_pk_fma_f32 v[62:63], v[18:19], v[18:19], v[62:63] op_sel_hi:[1,1,0]
	s_waitcnt vmcnt(0)
	v_lshlrev_b32_e32 v64, 16, v50
	v_and_b32_e32 v65, 0xffff0000, v50
	v_lshlrev_b32_e32 v50, 16, v51
	v_and_b32_e32 v51, 0xffff0000, v51
	v_pk_mul_f32 v[64:65], v[42:43], v[64:65] op_sel_hi:[0,1]
	v_pk_mul_f32 v[50:51], v[42:43], v[50:51] op_sel_hi:[0,1]
	s_waitcnt lgkmcnt(0)
	v_pk_fma_f32 v[2:3], v[56:57], v[50:51], v[2:3]
	v_pk_fma_f32 v[0:1], v[54:55], v[64:65], v[0:1]
	v_mul_f32_e32 v61, v2, v2
	v_mul_f32_e32 v53, v0, v0
	v_mul_f32_e32 v59, v1, v1
	v_mul_f32_e32 v63, v3, v3
	v_pk_add_f32 v[50:51], v[52:53], v[58:59]
	v_pk_add_f32 v[52:53], v[60:61], v[62:63]
	s_nop 0
	v_pk_add_f32 v[50:51], v[50:51], v[52:53]
	s_nop 0
	v_add_f32_e32 v42, v50, v51
	ds_bpermute_b32 v50, v43, v42
	s_waitcnt lgkmcnt(0)
	v_add_f32_e32 v42, v42, v50
	ds_bpermute_b32 v50, v44, v42
	s_waitcnt lgkmcnt(0)
	v_add_f32_e32 v42, v42, v50
	ds_bpermute_b32 v50, v45, v42
	s_waitcnt lgkmcnt(0)
	v_add_f32_e32 v42, v42, v50
	ds_bpermute_b32 v50, v46, v42
	s_waitcnt lgkmcnt(0)
	v_add_f32_e32 v42, v42, v50
	ds_bpermute_b32 v50, v47, v42
	s_waitcnt lgkmcnt(0)
	v_add_f32_e32 v42, v42, v50
	ds_bpermute_b32 v50, v48, v42
	s_waitcnt lgkmcnt(0)
	v_add_f32_e32 v42, v42, v50
	v_fmamk_f32 v42, v42, 0x3a000000, v33
	v_mul_f32_e32 v50, 0x4b800000, v42
	v_cmp_gt_f32_e64 s[0:1], s3, v42
	s_nop 1
	v_cndmask_b32_e64 v42, v42, v50, s[0:1]
	v_rsq_f32_e32 v42, v42
	ds_read_b128 v[50:53], v49
	ds_read_b128 v[54:57], v49 offset:8192
	global_store_dwordx4 v[36:37], v[0:3], off offset:3072 nt
	v_lshl_add_u64 v[36:37], v[36:37], 0, s[12:13]
	v_mul_f32_e32 v58, 0x45800000, v42
	v_cndmask_b32_e64 v42, v42, v58, s[0:1]
	v_pk_mul_f32 v[20:21], v[20:21], v[42:43] op_sel_hi:[1,0]
	v_pk_mul_f32 v[22:23], v[22:23], v[42:43] op_sel_hi:[1,0]
	s_waitcnt lgkmcnt(0)
; #define LAS __attribute__((address_space(3)))
; __device__ __forceinline__ unsigned cvt_pk_bf16(float lo, float hi) { unsigned r; asm volatile("v_cvt_pk_bf16_f32 %0, %1, %2" : "=v"(r) : "v"(lo), "v"(hi)); return r; }
; template <bool POST, bool PRE>
; __device__ __forceinline__ void row_core(const Params& P, const RowCfg& c, LAS float* vA, LAS float* vB, LAS float* vP, const bf16_t* RAW, const float* SSQ, bf16_t* H, int row, int lane, f32x4 (&v)[8]) {
;     const f32x4* xs = (const f32x4*)(c.xsrc + (size_t)row * DM) + lane;
; #pragma unroll
;     for (int j = 0; j < 8; ++j) v[j] = xs[64 * j];
;     if (POST) {
;         const u32x2* rs = (const u32x2*)(RAW + (size_t)row * DM) + lane;
;         float s = (lane < 32) ? SSQ[(size_t)row * 32 + lane] : 0.f; s = wave_sum(s);
;     ...
;         for (int j = 0; j < 8; ++j) { const f32x4 a = *(const LAS f32x4*)(vA + j * 256 + lane * 4), b = *(const LAS f32x4*)(vB + j * 256 + lane * 4);
;             v[j] = v[j] * rstd2 * a + b; u32x2 w; w.x = cvt_pk_bf16(v[j][0], v[j][1]); w.y = cvt_pk_bf16(v[j][2], v[j][3]); hs[64 * j] = w; }
	v_pk_fma_f32 v[20:21], v[50:51], v[20:21], v[54:55]
	v_pk_fma_f32 v[22:23], v[52:53], v[22:23], v[56:57]
	v_cvt_pk_bf16_f32 v54, v20, v21
	v_add_co_u32_e64 v40, s[0:1], s9, v40
	v_cvt_pk_bf16_f32 v55, v22, v23
	ds_read_b128 v[20:23], v49 offset:1024
	ds_read_b128 v[50:53], v49 offset:9216
	v_pk_mul_f32 v[12:13], v[12:13], v[42:43] op_sel_hi:[1,0]
	v_pk_mul_f32 v[14:15], v[14:15], v[42:43] op_sel_hi:[1,0]
	v_addc_co_u32_e64 v41, s[0:1], 0, v41, s[0:1]
	s_waitcnt lgkmcnt(0)
	v_pk_fma_f32 v[14:15], v[22:23], v[14:15], v[52:53]
	v_pk_fma_f32 v[12:13], v[20:21], v[12:13], v[50:51]
	global_store_dwordx2 v[40:41], v[54:55], off
	v_cvt_pk_bf16_f32 v50, v12, v13
	v_cvt_pk_bf16_f32 v51, v14, v15
	ds_read_b128 v[12:15], v49 offset:2048
	ds_read_b128 v[20:23], v49 offset:10240
	v_pk_mul_f32 v[28:29], v[28:29], v[42:43] op_sel_hi:[1,0]
	v_pk_mul_f32 v[30:31], v[30:31], v[42:43] op_sel_hi:[1,0]
	global_store_dwordx2 v[40:41], v[50:51], off offset:512
	v_pk_mul_f32 v[24:25], v[24:25], v[42:43] op_sel_hi:[1,0]
	s_waitcnt lgkmcnt(0)
	v_pk_fma_f32 v[14:15], v[14:15], v[30:31], v[22:23]
	v_pk_fma_f32 v[12:13], v[12:13], v[28:29], v[20:21]
	v_pk_mul_f32 v[26:27], v[26:27], v[42:43] op_sel_hi:[1,0]
	v_cvt_pk_bf16_f32 v28, v12, v13
	v_cvt_pk_bf16_f32 v29, v14, v15
	ds_read_b128 v[12:15], v49 offset:3072
	ds_read_b128 v[20:23], v49 offset:11264
	global_store_dwordx2 v[40:41], v[28:29], off offset:1024
	v_pk_mul_f32 v[4:5], v[4:5], v[42:43] op_sel_hi:[1,0]
	v_pk_mul_f32 v[6:7], v[6:7], v[42:43] op_sel_hi:[1,0]
	v_pk_mul_f32 v[8:9], v[8:9], v[42:43] op_sel_hi:[1,0]
	s_waitcnt lgkmcnt(0)
	v_pk_fma_f32 v[14:15], v[14:15], v[26:27], v[22:23]
	v_pk_fma_f32 v[12:13], v[12:13], v[24:25], v[20:21]
	v_pk_mul_f32 v[10:11], v[10:11], v[42:43] op_sel_hi:[1,0]
	v_cvt_pk_bf16_f32 v24, v12, v13
	v_cvt_pk_bf16_f32 v25, v14, v15
	ds_read_b128 v[12:15], v49 offset:4096
	ds_read_b128 v[20:23], v49 offset:12288
	global_store_dwordx2 v[40:41], v[24:25], off offset:1536
	v_pk_mul_f32 v[0:1], v[0:1], v[42:43] op_sel_hi:[1,0]
	v_pk_mul_f32 v[2:3], v[2:3], v[42:43] op_sel_hi:[1,0]
	s_waitcnt lgkmcnt(0)
	v_pk_fma_f32 v[6:7], v[14:15], v[6:7], v[22:23]
	v_pk_fma_f32 v[4:5], v[12:13], v[4:5], v[20:21]
	s_nop 0
	v_cvt_pk_bf16_f32 v20, v4, v5
	v_cvt_pk_bf16_f32 v21, v6, v7
	ds_read_b128 v[4:7], v49 offset:5120
	ds_read_b128 v[12:15], v49 offset:13312
	global_store_dwordx2 v[40:41], v[20:21], off offset:2048
	s_waitcnt lgkmcnt(0)
	v_pk_fma_f32 v[6:7], v[10:11], v[6:7], v[14:15]
	v_pk_fma_f32 v[4:5], v[8:9], v[4:5], v[12:13]
	v_pk_mul_f32 v[14:15], v[16:17], v[42:43] op_sel_hi:[1,0]
	v_cvt_pk_bf16_f32 v12, v4, v5
	v_cvt_pk_bf16_f32 v13, v6, v7
	ds_read_b128 v[4:7], v49 offset:6144
	ds_read_b128 v[8:11], v49 offset:14336
	v_pk_mul_f32 v[16:17], v[18:19], v[42:43] op_sel_hi:[1,0]
	global_store_dwordx2 v[40:41], v[12:13], off offset:2560
	s_waitcnt lgkmcnt(0)
	v_pk_fma_f32 v[6:7], v[16:17], v[6:7], v[10:11]
	v_pk_fma_f32 v[4:5], v[14:15], v[4:5], v[8:9]
	s_nop 0
	v_cvt_pk_bf16_f32 v12, v4, v5
	v_cvt_pk_bf16_f32 v13, v6, v7
	ds_read_b128 v[4:7], v49 offset:7168
	ds_read_b128 v[8:11], v49 offset:15360
	global_store_dwordx2 v[40:41], v[12:13], off offset:3072
	s_waitcnt lgkmcnt(0)
	v_pk_fma_f32 v[0:1], v[0:1], v[4:5], v[8:9]
	v_pk_fma_f32 v[2:3], v[2:3], v[6:7], v[10:11]
	v_cvt_pk_bf16_f32 v0, v0, v1
	s_nop 0
	v_cvt_pk_bf16_f32 v1, v2, v3
	global_store_dwordx2 v[40:41], v[0:1], off offset:3584
	s_cbranch_scc0 .LBB0_2056
.LBB0_2054:
	global_load_dwordx4 v[20:23], v[36:37], off offset:-4096 nt
	global_load_dwordx4 v[12:15], v[36:37], off offset:-3072 nt
	global_load_dwordx4 v[28:31], v[36:37], off offset:-2048 nt
	global_load_dwordx4 v[24:27], v[36:37], off offset:-1024 nt
	global_load_dwordx4 v[4:7], v[36:37], off nt
	global_load_dwordx4 v[8:11], v[36:37], off offset:1024 nt
	global_load_dwordx4 v[16:19], v[36:37], off offset:2048 nt
	global_load_dwordx4 v[0:3], v[36:37], off offset:3072 nt
	v_mov_b32_e32 v42, 0
	s_and_saveexec_b64 s[0:1], vcc
	s_cbranch_execz .LBB0_2053
	v_lshl_add_u64 v[40:41], s[92:93], 0, v[34:35]
	global_load_dword v42, v[40:41], off
	s_branch .LBB0_2053

; #define LAS __attribute__((address_space(3)))
; template <bool POST, bool PRE>
; __device__ __forceinline__ void row_core(const Params& P, const RowCfg& c, LAS float* vA, LAS float* vB, LAS float* vP, const bf16_t* RAW, const float* SSQ, bf16_t* H, int row, int lane, f32x4 (&v)[8]) {
;     const f32x4* xs = (const f32x4*)(c.xsrc + (size_t)row * DM) + lane;
; #pragma unroll
;     for (int j = 0; j < 8; ++j) v[j] = xs[64 * j];
;     if (POST) {
;         const u32x2* rs = (const u32x2*)(RAW + (size_t)row * DM) + lane;
;         float s = (lane < 32) ? SSQ[(size_t)row * 32 + lane] : 0.f; s = wave_sum(s);
;         const float rstd = rsqrtf(s * (1.0f / DM) + EPS);
;         f32x4* os = (f32x4*)(P.out + (size_t)row * DM) + lane;
; #pragma unroll
;         for (int j = 0; j < 8; ++j) { const u32x2 rb = rs[64 * j]; const f32x4 r = (f32x4){__uint_as_float(rb.x << 16), __uint_as_float(rb.x & 0xffff0000u), __uint_as_float(rb.y << 16), __uint_as_float(rb.y & 0xffff0000u)};
;             const f32x4 pv = *(const LAS f32x4*)(vP + j * 256 + lane * 4); v[j] += r * rstd * pv; os[64 * j] = v[j]; }
.LBB0_2275:
	s_or_b64 exec, exec, s[0:1]
	v_lshl_add_u64 v[78:79], s[92:93], 0, v[68:69]
	v_add_co_u32_e64 v78, s[0:1], s5, v78
	s_waitcnt vmcnt(0)
	ds_bpermute_b32 v82, v70, v77
	v_addc_co_u32_e64 v79, s[0:1], 0, v79, s[0:1]
	global_load_dwordx2 v[80:81], v[78:79], off
	s_add_i32 s2, s2, s4
	s_waitcnt lgkmcnt(0)
	v_add_f32_e32 v77, v77, v82
	ds_bpermute_b32 v82, v71, v77
	v_lshl_add_u64 v[64:65], v[64:65], 0, s[6:7]
	s_cmpk_lt_i32 s2, 0x4000
	v_lshl_add_u64 v[68:69], v[68:69], 0, s[10:11]
	s_waitcnt lgkmcnt(0)
	v_add_f32_e32 v77, v77, v82
	ds_bpermute_b32 v82, v72, v77
	s_waitcnt lgkmcnt(0)
	v_add_f32_e32 v77, v77, v82
	ds_bpermute_b32 v82, v73, v77
	s_waitcnt lgkmcnt(0)
	v_add_f32_e32 v77, v77, v82
	ds_bpermute_b32 v82, v74, v77
	s_waitcnt lgkmcnt(0)
	v_add_f32_e32 v77, v77, v82
	ds_bpermute_b32 v82, v75, v77
	s_waitcnt lgkmcnt(0)
	v_add_f32_e32 v77, v77, v82
	v_fmamk_f32 v77, v77, 0x3a000000, v76
	v_mul_f32_e32 v82, 0x4b800000, v77
	v_cmp_gt_f32_e64 s[0:1], s3, v77
	s_waitcnt vmcnt(0)
	v_lshlrev_b32_e32 v84, 16, v80
	v_cndmask_b32_e64 v77, v77, v82, s[0:1]
	v_rsq_f32_e32 v77, v77
	v_and_b32_e32 v85, 0xffff0000, v80
	v_lshlrev_b32_e32 v80, 16, v81
	v_and_b32_e32 v81, 0xffff0000, v81
	v_mul_f32_e32 v82, 0x45800000, v77
	v_cndmask_b32_e64 v82, v77, v82, s[0:1]
	v_pk_mul_f32 v[84:85], v[82:83], v[84:85] op_sel_hi:[0,1]
	v_pk_mul_f32 v[80:81], v[82:83], v[80:81] op_sel_hi:[0,1]
	v_pk_fma_f32 v[62:63], v[2:3], v[80:81], v[62:63]
	v_pk_fma_f32 v[60:61], v[0:1], v[84:85], v[60:61]
	global_store_dwordx4 v[66:67], v[60:63], off offset:-4096 nt
	global_load_dwordx2 v[60:61], v[78:79], off offset:512
	s_waitcnt vmcnt(0)
	v_lshlrev_b32_e32 v62, 16, v60
	v_and_b32_e32 v63, 0xffff0000, v60
	v_lshlrev_b32_e32 v60, 16, v61
	v_and_b32_e32 v61, 0xffff0000, v61
	v_pk_mul_f32 v[62:63], v[82:83], v[62:63] op_sel_hi:[0,1]
	v_pk_mul_f32 v[60:61], v[82:83], v[60:61] op_sel_hi:[0,1]
	v_pk_fma_f32 v[58:59], v[6:7], v[60:61], v[58:59]
	v_pk_fma_f32 v[56:57], v[4:5], v[62:63], v[56:57]
	global_store_dwordx4 v[66:67], v[56:59], off offset:-3072 nt
	global_load_dwordx2 v[56:57], v[78:79], off offset:1024
	s_waitcnt vmcnt(0)
	v_lshlrev_b32_e32 v58, 16, v56
	v_and_b32_e32 v59, 0xffff0000, v56
	v_lshlrev_b32_e32 v56, 16, v57
	v_and_b32_e32 v57, 0xffff0000, v57
	v_pk_mul_f32 v[58:59], v[82:83], v[58:59] op_sel_hi:[0,1]
	v_pk_mul_f32 v[56:57], v[82:83], v[56:57] op_sel_hi:[0,1]
	v_pk_fma_f32 v[54:55], v[10:11], v[56:57], v[54:55]
	v_pk_fma_f32 v[52:53], v[8:9], v[58:59], v[52:53]
	global_store_dwordx4 v[66:67], v[52:55], off offset:-2048 nt
	global_load_dwordx2 v[52:53], v[78:79], off offset:1536
	s_waitcnt vmcnt(0)
	v_lshlrev_b32_e32 v54, 16, v52
	v_and_b32_e32 v55, 0xffff0000, v52
	v_lshlrev_b32_e32 v52, 16, v53
	v_and_b32_e32 v53, 0xffff0000, v53
	v_pk_mul_f32 v[54:55], v[82:83], v[54:55] op_sel_hi:[0,1]
	v_pk_mul_f32 v[52:53], v[82:83], v[52:53] op_sel_hi:[0,1]
	v_pk_fma_f32 v[50:51], v[14:15], v[52:53], v[50:51]
	v_pk_fma_f32 v[48:49], v[12:13], v[54:55], v[48:49]
	global_store_dwordx4 v[66:67], v[48:51], off offset:-1024 nt
	global_load_dwordx2 v[48:49], v[78:79], off offset:2048
	s_waitcnt vmcnt(0)
	v_lshlrev_b32_e32 v50, 16, v48
	v_and_b32_e32 v51, 0xffff0000, v48
	v_lshlrev_b32_e32 v48, 16, v49
	v_and_b32_e32 v49, 0xffff0000, v49
	v_pk_mul_f32 v[50:51], v[82:83], v[50:51] op_sel_hi:[0,1]
	v_pk_mul_f32 v[48:49], v[82:83], v[48:49] op_sel_hi:[0,1]
	v_pk_fma_f32 v[46:47], v[18:19], v[48:49], v[46:47]
	v_pk_fma_f32 v[44:45], v[16:17], v[50:51], v[44:45]
	global_store_dwordx4 v[66:67], v[44:47], off nt
	global_load_dwordx2 v[44:45], v[78:79], off offset:2560
	s_waitcnt vmcnt(0)
	v_lshlrev_b32_e32 v46, 16, v44
	v_and_b32_e32 v47, 0xffff0000, v44
	v_lshlrev_b32_e32 v44, 16, v45
	v_and_b32_e32 v45, 0xffff0000, v45
	v_pk_mul_f32 v[46:47], v[82:83], v[46:47] op_sel_hi:[0,1]
	v_pk_mul_f32 v[44:45], v[82:83], v[44:45] op_sel_hi:[0,1]
	v_pk_fma_f32 v[42:43], v[22:23], v[44:45], v[42:43]
	v_pk_fma_f32 v[40:41], v[20:21], v[46:47], v[40:41]
	global_store_dwordx4 v[66:67], v[40:43], off offset:1024 nt
	global_load_dwordx2 v[40:41], v[78:79], off offset:3072
	s_waitcnt vmcnt(0)
	v_lshlrev_b32_e32 v42, 16, v40
	v_and_b32_e32 v43, 0xffff0000, v40
	v_lshlrev_b32_e32 v40, 16, v41
	v_and_b32_e32 v41, 0xffff0000, v41
	v_pk_mul_f32 v[42:43], v[82:83], v[42:43] op_sel_hi:[0,1]
	v_pk_mul_f32 v[40:41], v[82:83], v[40:41] op_sel_hi:[0,1]
	v_pk_fma_f32 v[38:39], v[26:27], v[40:41], v[38:39]
	v_pk_fma_f32 v[36:37], v[24:25], v[42:43], v[36:37]
	global_store_dwordx4 v[66:67], v[36:39], off offset:2048 nt
	global_load_dwordx2 v[36:37], v[78:79], off offset:3584
	s_waitcnt vmcnt(0)
	v_lshlrev_b32_e32 v38, 16, v36
	v_and_b32_e32 v39, 0xffff0000, v36
	v_lshlrev_b32_e32 v36, 16, v37
	v_and_b32_e32 v37, 0xffff0000, v37
	v_pk_mul_f32 v[38:39], v[82:83], v[38:39] op_sel_hi:[0,1]
	v_pk_mul_f32 v[36:37], v[82:83], v[36:37] op_sel_hi:[0,1]
	v_pk_fma_f32 v[34:35], v[30:31], v[36:37], v[34:35]
	v_pk_fma_f32 v[32:33], v[28:29], v[38:39], v[32:33]
	global_store_dwordx4 v[66:67], v[32:35], off offset:3072 nt
	v_lshl_add_u64 v[66:67], v[66:67], 0, s[8:9]
	s_cbranch_scc0 .LBB0_2278
.LBB0_2276:
	global_load_dwordx4 v[60:63], v[66:67], off offset:-4096 nt
	global_load_dwordx4 v[56:59], v[66:67], off offset:-3072 nt
	global_load_dwordx4 v[52:55], v[66:67], off offset:-2048 nt
	global_load_dwordx4 v[48:51], v[66:67], off offset:-1024 nt
	global_load_dwordx4 v[44:47], v[66:67], off nt
	global_load_dwordx4 v[40:43], v[66:67], off offset:1024 nt
	global_load_dwordx4 v[36:39], v[66:67], off offset:2048 nt
	global_load_dwordx4 v[32:35], v[66:67], off offset:3072 nt
	v_mov_b32_e32 v77, 0
	s_and_saveexec_b64 s[0:1], vcc
	s_cbranch_execz .LBB0_2275
	v_lshl_add_u64 v[78:79], s[92:93], 0, v[64:65]
	global_load_dword v77, v[78:79], off
	s_branch .LBB0_2275
